# GEMM K-loops: priority raised before the MFMA segment's opening barrier instead of after it
# baseline (speedup 1.0000x reference)
.LBB0_265:
	ds_read_b128 v[142:145], v151
	ds_read_b128 v[146:149], v151 offset:1024
	ds_read_b128 v[154:157], v151 offset:2048
	ds_read_b128 v[158:161], v151 offset:3072
	ds_read_b128 v[162:165], v152
	ds_read_b128 v[166:169], v152 offset:1024
	ds_read_b128 v[176:179], v152 offset:2048
	ds_read_b128 v[180:183], v152 offset:3072
	s_add_u32 s28, s0, 0xfff00080
	s_addc_u32 s29, s1, -1
	s_cmp_eq_u32 s52, 60
	s_cselect_b32 s31, s33, s29
	s_cselect_b32 s30, s47, s28
	s_cselect_b32 s29, s48, s51
	s_cselect_b32 s28, s49, s50
	v_lshl_add_u64 v[170:171], s[0:1], 0, v[138:139]
	s_add_i32 m0, s5, 0xc000
	ds_read_b128 v[184:187], v153
	ds_read_b128 v[188:191], v153 offset:1024
	ds_read_b128 v[192:195], v153 offset:2048
	ds_read_b128 v[196:199], v153 offset:3072
	ds_read_b128 v[200:203], v153 offset:4096
	ds_read_b128 v[204:207], v153 offset:5120
	ds_read_b128 v[208:211], v153 offset:6144
	ds_read_b128 v[212:215], v153 offset:7168
	global_load_lds_dwordx4 v[170:171], off
	v_lshl_add_u64 v[170:171], s[0:1], 0, v[140:141]
	s_add_i32 m0, s5, 0xe000
	s_nop 0
	global_load_lds_dwordx4 v[170:171], off
	s_waitcnt vmcnt(8)
	s_waitcnt lgkmcnt(0)
	s_setprio 1
	s_barrier
	v_mfma_f32_16x16x32_bf16 v[126:129], v[142:145], v[184:187], v[126:129]
	v_mfma_f32_16x16x32_bf16 v[122:125], v[154:157], v[184:187], v[122:125]
	v_mfma_f32_16x16x32_bf16 v[110:113], v[142:145], v[192:195], v[110:113]
	v_mfma_f32_16x16x32_bf16 v[106:109], v[154:157], v[192:195], v[106:109]
	v_mfma_f32_16x16x32_bf16 v[94:97], v[142:145], v[200:203], v[94:97]
	v_mfma_f32_16x16x32_bf16 v[90:93], v[154:157], v[200:203], v[90:93]
	v_mfma_f32_16x16x32_bf16 v[78:81], v[142:145], v[208:211], v[78:81]
	v_mfma_f32_16x16x32_bf16 v[74:77], v[154:157], v[208:211], v[74:77]
	v_mfma_f32_16x16x32_bf16 v[126:129], v[146:149], v[188:191], v[126:129]
	v_mfma_f32_16x16x32_bf16 v[122:125], v[158:161], v[188:191], v[122:125]
	v_mfma_f32_16x16x32_bf16 v[110:113], v[146:149], v[196:199], v[110:113]
	v_mfma_f32_16x16x32_bf16 v[106:109], v[158:161], v[196:199], v[106:109]
	v_mfma_f32_16x16x32_bf16 v[94:97], v[146:149], v[204:207], v[94:97]
	v_mfma_f32_16x16x32_bf16 v[90:93], v[158:161], v[204:207], v[90:93]
	v_mfma_f32_16x16x32_bf16 v[78:81], v[146:149], v[212:215], v[78:81]
	v_mfma_f32_16x16x32_bf16 v[74:77], v[158:161], v[212:215], v[74:77]
	s_setprio 0
	s_setprio 1
	v_mfma_f32_16x16x32_bf16 v[118:121], v[162:165], v[184:187], v[118:121]
	v_mfma_f32_16x16x32_bf16 v[114:117], v[176:179], v[184:187], v[114:117]
	v_mfma_f32_16x16x32_bf16 v[102:105], v[162:165], v[192:195], v[102:105]
	v_mfma_f32_16x16x32_bf16 v[98:101], v[176:179], v[192:195], v[98:101]
	v_mfma_f32_16x16x32_bf16 v[86:89], v[162:165], v[200:203], v[86:89]
	v_mfma_f32_16x16x32_bf16 v[82:85], v[176:179], v[200:203], v[82:85]
	v_mfma_f32_16x16x32_bf16 v[70:73], v[162:165], v[208:211], v[70:73]
	v_mfma_f32_16x16x32_bf16 v[66:69], v[176:179], v[208:211], v[66:69]
	v_mfma_f32_16x16x32_bf16 v[118:121], v[166:169], v[188:191], v[118:121]
	v_mfma_f32_16x16x32_bf16 v[114:117], v[180:183], v[188:191], v[114:117]
	v_mfma_f32_16x16x32_bf16 v[102:105], v[166:169], v[196:199], v[102:105]
	v_mfma_f32_16x16x32_bf16 v[98:101], v[180:183], v[196:199], v[98:101]
	v_mfma_f32_16x16x32_bf16 v[86:89], v[166:169], v[204:207], v[86:89]
	v_mfma_f32_16x16x32_bf16 v[82:85], v[180:183], v[204:207], v[82:85]
	v_mfma_f32_16x16x32_bf16 v[70:73], v[166:169], v[212:215], v[70:73]
	v_mfma_f32_16x16x32_bf16 v[66:69], v[180:183], v[212:215], v[66:69]
	s_setprio 0
	s_barrier
	s_add_i32 s53, s43, s24
	v_lshl_add_u64 v[170:171], s[28:29], 0, v[134:135]
	s_mov_b32 m0, s53
	ds_read_b128 v[184:187], v153 offset:16384
	ds_read_b128 v[188:191], v153 offset:17408
	ds_read_b128 v[192:195], v153 offset:18432
	ds_read_b128 v[196:199], v153 offset:19456
	ds_read_b128 v[200:203], v153 offset:20480
	ds_read_b128 v[204:207], v153 offset:21504
	ds_read_b128 v[208:211], v153 offset:22528
	ds_read_b128 v[212:215], v153 offset:23552
	global_load_lds_dwordx4 v[170:171], off
	s_add_i32 m0, s53, 0x2000
	s_add_u32 s54, s28, 0x100000
	v_lshl_add_u64 v[216:217], s[28:29], 0, v[130:131]
	s_addc_u32 s55, s29, 0
	s_add_i32 s53, s44, s24
	global_load_lds_dwordx4 v[216:217], off
	v_lshl_add_u64 v[218:219], s[54:55], 0, v[134:135]
	s_mov_b32 m0, s53
	v_lshl_add_u64 v[220:221], s[30:31], 0, v[132:133]
	global_load_lds_dwordx4 v[218:219], off
	v_lshl_add_u64 v[218:219], s[54:55], 0, v[130:131]
	s_add_i32 m0, s53, 0x2000
	s_nop 0
	global_load_lds_dwordx4 v[218:219], off
	v_lshl_add_u64 v[218:219], s[30:31], 0, v[136:137]
	s_mov_b32 m0, s5
	s_nop 0
	global_load_lds_dwordx4 v[218:219], off
	s_mov_b32 m0, s34
	s_nop 0
	global_load_lds_dwordx4 v[220:221], off
	s_waitcnt vmcnt(8)
	s_waitcnt lgkmcnt(0)
	s_setprio 1
	s_barrier
	v_mfma_f32_16x16x32_bf16 v[62:65], v[142:145], v[184:187], v[62:65]
	v_mfma_f32_16x16x32_bf16 v[58:61], v[154:157], v[184:187], v[58:61]
	v_mfma_f32_16x16x32_bf16 v[46:49], v[142:145], v[192:195], v[46:49]
	v_mfma_f32_16x16x32_bf16 v[42:45], v[154:157], v[192:195], v[42:45]
	v_mfma_f32_16x16x32_bf16 v[30:33], v[142:145], v[200:203], v[30:33]
	v_mfma_f32_16x16x32_bf16 v[26:29], v[154:157], v[200:203], v[26:29]
	v_mfma_f32_16x16x32_bf16 v[14:17], v[142:145], v[208:211], v[14:17]
	v_mfma_f32_16x16x32_bf16 v[10:13], v[154:157], v[208:211], v[10:13]
	v_mfma_f32_16x16x32_bf16 v[62:65], v[146:149], v[188:191], v[62:65]
	v_mfma_f32_16x16x32_bf16 v[58:61], v[158:161], v[188:191], v[58:61]
	v_mfma_f32_16x16x32_bf16 v[46:49], v[146:149], v[196:199], v[46:49]
	v_mfma_f32_16x16x32_bf16 v[42:45], v[158:161], v[196:199], v[42:45]
	v_mfma_f32_16x16x32_bf16 v[30:33], v[146:149], v[204:207], v[30:33]
	v_mfma_f32_16x16x32_bf16 v[26:29], v[158:161], v[204:207], v[26:29]
	v_mfma_f32_16x16x32_bf16 v[14:17], v[146:149], v[212:215], v[14:17]
	v_mfma_f32_16x16x32_bf16 v[10:13], v[158:161], v[212:215], v[10:13]
	s_setprio 0
	s_setprio 1
	v_mfma_f32_16x16x32_bf16 v[54:57], v[162:165], v[184:187], v[54:57]
	v_mfma_f32_16x16x32_bf16 v[50:53], v[176:179], v[184:187], v[50:53]
	v_mfma_f32_16x16x32_bf16 v[38:41], v[162:165], v[192:195], v[38:41]
	v_mfma_f32_16x16x32_bf16 v[34:37], v[176:179], v[192:195], v[34:37]
	v_mfma_f32_16x16x32_bf16 v[22:25], v[162:165], v[200:203], v[22:25]
	v_mfma_f32_16x16x32_bf16 v[18:21], v[176:179], v[200:203], v[18:21]
	v_mfma_f32_16x16x32_bf16 v[6:9], v[162:165], v[208:211], v[6:9]
	v_mfma_f32_16x16x32_bf16 v[2:5], v[176:179], v[208:211], v[2:5]
	v_mfma_f32_16x16x32_bf16 v[54:57], v[166:169], v[188:191], v[54:57]
	v_mfma_f32_16x16x32_bf16 v[50:53], v[180:183], v[188:191], v[50:53]
	v_mfma_f32_16x16x32_bf16 v[38:41], v[166:169], v[196:199], v[38:41]
	v_mfma_f32_16x16x32_bf16 v[34:37], v[180:183], v[196:199], v[34:37]
	v_mfma_f32_16x16x32_bf16 v[22:25], v[166:169], v[204:207], v[22:25]
	v_mfma_f32_16x16x32_bf16 v[18:21], v[180:183], v[204:207], v[18:21]
	v_mfma_f32_16x16x32_bf16 v[6:9], v[166:169], v[212:215], v[6:9]
	v_mfma_f32_16x16x32_bf16 v[2:5], v[180:183], v[212:215], v[2:5]
	s_setprio 0
	s_barrier
	s_add_i32 s53, 0, 0x18000
	s_add_i32 s54, 0, 0x1c000
	v_add_u32_e32 v158, s53, v150
	v_add_u32_e32 v180, s54, v150
	ds_read_b128 v[142:145], v158
	ds_read_b128 v[146:149], v158 offset:1024
	ds_read_b128 v[154:157], v158 offset:2048
	ds_read_b128 v[158:161], v158 offset:3072
	ds_read_b128 v[162:165], v180
	ds_read_b128 v[166:169], v180 offset:1024
	ds_read_b128 v[176:179], v180 offset:2048
	ds_read_b128 v[180:183], v180 offset:3072
	s_add_u32 s30, s30, 0x100000
	s_addc_u32 s31, s31, 0
	s_mov_b32 m0, s35
	v_lshl_add_u64 v[222:223], s[30:31], 0, v[136:137]
	ds_read_b128 v[184:187], v153 offset:32768
	ds_read_b128 v[188:191], v153 offset:33792
	ds_read_b128 v[192:195], v153 offset:34816
	ds_read_b128 v[196:199], v153 offset:35840
	ds_read_b128 v[200:203], v153 offset:36864
	ds_read_b128 v[204:207], v153 offset:37888
	ds_read_b128 v[208:211], v153 offset:38912
	ds_read_b128 v[212:215], v153 offset:39936
	global_load_lds_dwordx4 v[222:223], off
	v_lshl_add_u64 v[222:223], s[30:31], 0, v[132:133]
	s_mov_b32 m0, s37
	s_nop 0
	global_load_lds_dwordx4 v[222:223], off
	s_waitcnt vmcnt(8)
	s_waitcnt lgkmcnt(0)
	s_setprio 1
	s_barrier
	v_mfma_f32_16x16x32_bf16 v[126:129], v[142:145], v[184:187], v[126:129]
	v_mfma_f32_16x16x32_bf16 v[122:125], v[154:157], v[184:187], v[122:125]
	v_mfma_f32_16x16x32_bf16 v[110:113], v[142:145], v[192:195], v[110:113]
	v_mfma_f32_16x16x32_bf16 v[106:109], v[154:157], v[192:195], v[106:109]
	v_mfma_f32_16x16x32_bf16 v[94:97], v[142:145], v[200:203], v[94:97]
	v_mfma_f32_16x16x32_bf16 v[90:93], v[154:157], v[200:203], v[90:93]
	v_mfma_f32_16x16x32_bf16 v[78:81], v[142:145], v[208:211], v[78:81]
	v_mfma_f32_16x16x32_bf16 v[74:77], v[154:157], v[208:211], v[74:77]
	v_mfma_f32_16x16x32_bf16 v[126:129], v[146:149], v[188:191], v[126:129]
	v_mfma_f32_16x16x32_bf16 v[122:125], v[158:161], v[188:191], v[122:125]
	v_mfma_f32_16x16x32_bf16 v[110:113], v[146:149], v[196:199], v[110:113]
	v_mfma_f32_16x16x32_bf16 v[106:109], v[158:161], v[196:199], v[106:109]
	v_mfma_f32_16x16x32_bf16 v[94:97], v[146:149], v[204:207], v[94:97]
	v_mfma_f32_16x16x32_bf16 v[90:93], v[158:161], v[204:207], v[90:93]
	v_mfma_f32_16x16x32_bf16 v[78:81], v[146:149], v[212:215], v[78:81]
	v_mfma_f32_16x16x32_bf16 v[74:77], v[158:161], v[212:215], v[74:77]
	s_setprio 0
	s_setprio 1
	v_mfma_f32_16x16x32_bf16 v[118:121], v[162:165], v[184:187], v[118:121]
	v_mfma_f32_16x16x32_bf16 v[114:117], v[176:179], v[184:187], v[114:117]
	v_mfma_f32_16x16x32_bf16 v[102:105], v[162:165], v[192:195], v[102:105]
	v_mfma_f32_16x16x32_bf16 v[98:101], v[176:179], v[192:195], v[98:101]
	v_mfma_f32_16x16x32_bf16 v[86:89], v[162:165], v[200:203], v[86:89]
	v_mfma_f32_16x16x32_bf16 v[82:85], v[176:179], v[200:203], v[82:85]
	v_mfma_f32_16x16x32_bf16 v[70:73], v[162:165], v[208:211], v[70:73]
	v_mfma_f32_16x16x32_bf16 v[66:69], v[176:179], v[208:211], v[66:69]
	v_mfma_f32_16x16x32_bf16 v[118:121], v[166:169], v[188:191], v[118:121]
	v_mfma_f32_16x16x32_bf16 v[114:117], v[180:183], v[188:191], v[114:117]
	v_mfma_f32_16x16x32_bf16 v[102:105], v[166:169], v[196:199], v[102:105]
	v_mfma_f32_16x16x32_bf16 v[98:101], v[180:183], v[196:199], v[98:101]
	v_mfma_f32_16x16x32_bf16 v[86:89], v[166:169], v[204:207], v[86:89]
	v_mfma_f32_16x16x32_bf16 v[82:85], v[180:183], v[204:207], v[82:85]
	v_mfma_f32_16x16x32_bf16 v[70:73], v[166:169], v[212:215], v[70:73]
	v_mfma_f32_16x16x32_bf16 v[66:69], v[180:183], v[212:215], v[66:69]
	s_setprio 0
	s_barrier
	s_add_i32 s30, s53, s24
	v_lshl_add_u64 v[170:171], v[170:171], 0, s[12:13]
	s_mov_b32 m0, s30
	ds_read_b128 v[184:187], v153 offset:49152
	ds_read_b128 v[188:191], v153 offset:50176
	ds_read_b128 v[192:195], v153 offset:51200
	ds_read_b128 v[196:199], v153 offset:52224
	ds_read_b128 v[200:203], v153 offset:53248
	ds_read_b128 v[204:207], v153 offset:54272
	ds_read_b128 v[208:211], v153 offset:55296
	ds_read_b128 v[212:215], v153 offset:56320
	global_load_lds_dwordx4 v[170:171], off
	s_add_i32 m0, s30, 0x2000
	s_add_u32 s28, s28, 0x100080
	v_lshl_add_u64 v[170:171], v[216:217], 0, s[12:13]
	s_addc_u32 s29, s29, 0
	s_add_i32 s30, s54, s24
	global_load_lds_dwordx4 v[170:171], off
	v_lshl_add_u64 v[170:171], s[28:29], 0, v[134:135]
	s_mov_b32 m0, s30
	s_nop 0
	global_load_lds_dwordx4 v[170:171], off
	v_lshl_add_u64 v[170:171], s[28:29], 0, v[130:131]
	s_add_i32 m0, s30, 0x2000
	s_nop 0
	global_load_lds_dwordx4 v[170:171], off
	v_lshl_add_u64 v[170:171], v[218:219], 0, s[12:13]
	s_mov_b32 m0, s41
	s_nop 0
	global_load_lds_dwordx4 v[170:171], off
	v_lshl_add_u64 v[170:171], v[220:221], 0, s[12:13]
	s_mov_b32 m0, s42
	s_nop 0
	global_load_lds_dwordx4 v[170:171], off
	s_waitcnt vmcnt(8)
	s_waitcnt lgkmcnt(0)
	s_setprio 1
	s_barrier
	v_mfma_f32_16x16x32_bf16 v[62:65], v[142:145], v[184:187], v[62:65]
	v_mfma_f32_16x16x32_bf16 v[58:61], v[154:157], v[184:187], v[58:61]
	v_mfma_f32_16x16x32_bf16 v[46:49], v[142:145], v[192:195], v[46:49]
	v_mfma_f32_16x16x32_bf16 v[42:45], v[154:157], v[192:195], v[42:45]
	v_mfma_f32_16x16x32_bf16 v[30:33], v[142:145], v[200:203], v[30:33]
	v_mfma_f32_16x16x32_bf16 v[26:29], v[154:157], v[200:203], v[26:29]
	v_mfma_f32_16x16x32_bf16 v[14:17], v[142:145], v[208:211], v[14:17]
	v_mfma_f32_16x16x32_bf16 v[10:13], v[154:157], v[208:211], v[10:13]
	v_mfma_f32_16x16x32_bf16 v[62:65], v[146:149], v[188:191], v[62:65]
	v_mfma_f32_16x16x32_bf16 v[58:61], v[158:161], v[188:191], v[58:61]
	v_mfma_f32_16x16x32_bf16 v[46:49], v[146:149], v[196:199], v[46:49]
	v_mfma_f32_16x16x32_bf16 v[42:45], v[158:161], v[196:199], v[42:45]
	v_mfma_f32_16x16x32_bf16 v[30:33], v[146:149], v[204:207], v[30:33]
	v_mfma_f32_16x16x32_bf16 v[26:29], v[158:161], v[204:207], v[26:29]
	v_mfma_f32_16x16x32_bf16 v[14:17], v[146:149], v[212:215], v[14:17]
	v_mfma_f32_16x16x32_bf16 v[10:13], v[158:161], v[212:215], v[10:13]
	s_setprio 0
	s_setprio 1
	v_mfma_f32_16x16x32_bf16 v[54:57], v[162:165], v[184:187], v[54:57]
	v_mfma_f32_16x16x32_bf16 v[50:53], v[176:179], v[184:187], v[50:53]
	v_mfma_f32_16x16x32_bf16 v[38:41], v[162:165], v[192:195], v[38:41]
	v_mfma_f32_16x16x32_bf16 v[34:37], v[176:179], v[192:195], v[34:37]
	v_mfma_f32_16x16x32_bf16 v[22:25], v[162:165], v[200:203], v[22:25]
	v_mfma_f32_16x16x32_bf16 v[18:21], v[176:179], v[200:203], v[18:21]
	v_mfma_f32_16x16x32_bf16 v[6:9], v[162:165], v[208:211], v[6:9]
	v_mfma_f32_16x16x32_bf16 v[2:5], v[176:179], v[208:211], v[2:5]
	v_mfma_f32_16x16x32_bf16 v[54:57], v[166:169], v[188:191], v[54:57]
	v_mfma_f32_16x16x32_bf16 v[50:53], v[180:183], v[188:191], v[50:53]
	v_mfma_f32_16x16x32_bf16 v[38:41], v[166:169], v[196:199], v[38:41]
	v_mfma_f32_16x16x32_bf16 v[34:37], v[180:183], v[196:199], v[34:37]
	v_mfma_f32_16x16x32_bf16 v[22:25], v[166:169], v[204:207], v[22:25]
	v_mfma_f32_16x16x32_bf16 v[18:21], v[180:183], v[204:207], v[18:21]
	v_mfma_f32_16x16x32_bf16 v[6:9], v[166:169], v[212:215], v[6:9]
	v_mfma_f32_16x16x32_bf16 v[2:5], v[180:183], v[212:215], v[2:5]
	s_setprio 0
	s_barrier
	s_add_i32 s52, s52, 2
	s_add_u32 s0, s0, 0x100
	s_addc_u32 s1, s1, 0
	s_add_u32 s50, s50, 0x100
	s_addc_u32 s51, s51, 0
	s_cmp_gt_u32 s52, 61
	s_cbranch_scc0 .LBB0_265
	s_and_b64 vcc, exec, s[14:15]
	s_cbranch_vccz .LBB0_268
	s_barrier

.LBB0_374:
	ds_read_b128 v[130:133], v188
	ds_read_b128 v[148:151], v188 offset:1024
	ds_read_b128 v[152:155], v188 offset:2048
	ds_read_b128 v[156:159], v188 offset:3072
	ds_read_b128 v[160:163], v189
	ds_read_b128 v[164:167], v189 offset:1024
	ds_read_b128 v[168:171], v189 offset:2048
	ds_read_b128 v[194:197], v189 offset:3072
	s_add_u32 s2, s0, 0xfff00080
	s_addc_u32 s3, s1, -1
	s_cmp_eq_u32 s43, 60
	s_cselect_b32 s39, s5, s3
	s_cselect_b32 s38, s6, s2
	s_cselect_b32 s3, s19, s42
	s_cselect_b32 s2, s21, s33
	v_lshl_add_u64 v[230:231], s[0:1], 0, v[144:145]
	s_add_i32 m0, s25, 0xc000
	ds_read_b128 v[198:201], v190
	ds_read_b128 v[202:205], v190 offset:1024
	ds_read_b128 v[206:209], v190 offset:2048
	ds_read_b128 v[210:213], v190 offset:3072
	ds_read_b128 v[214:217], v190 offset:4096
	ds_read_b128 v[218:221], v190 offset:5120
	ds_read_b128 v[222:225], v190 offset:6144
	ds_read_b128 v[226:229], v190 offset:7168
	global_load_lds_dwordx4 v[230:231], off
	v_lshl_add_u64 v[230:231], s[0:1], 0, v[146:147]
	s_add_i32 m0, s25, 0xe000
	s_nop 0
	global_load_lds_dwordx4 v[230:231], off
	s_waitcnt vmcnt(8)
	s_waitcnt lgkmcnt(0)
	s_setprio 1
	s_barrier
	v_mfma_f32_16x16x32_bf16 v[126:129], v[130:133], v[198:201], v[126:129]
	v_mfma_f32_16x16x32_bf16 v[122:125], v[152:155], v[198:201], v[122:125]
	v_mfma_f32_16x16x32_bf16 v[110:113], v[130:133], v[206:209], v[110:113]
	v_mfma_f32_16x16x32_bf16 v[106:109], v[152:155], v[206:209], v[106:109]
	v_mfma_f32_16x16x32_bf16 v[94:97], v[130:133], v[214:217], v[94:97]
	v_mfma_f32_16x16x32_bf16 v[90:93], v[152:155], v[214:217], v[90:93]
	v_mfma_f32_16x16x32_bf16 v[78:81], v[130:133], v[222:225], v[78:81]
	v_mfma_f32_16x16x32_bf16 v[74:77], v[152:155], v[222:225], v[74:77]
	v_mfma_f32_16x16x32_bf16 v[126:129], v[148:151], v[202:205], v[126:129]
	v_mfma_f32_16x16x32_bf16 v[122:125], v[156:159], v[202:205], v[122:125]
	v_mfma_f32_16x16x32_bf16 v[110:113], v[148:151], v[210:213], v[110:113]
	v_mfma_f32_16x16x32_bf16 v[106:109], v[156:159], v[210:213], v[106:109]
	v_mfma_f32_16x16x32_bf16 v[94:97], v[148:151], v[218:221], v[94:97]
	v_mfma_f32_16x16x32_bf16 v[90:93], v[156:159], v[218:221], v[90:93]
	v_mfma_f32_16x16x32_bf16 v[78:81], v[148:151], v[226:229], v[78:81]
	v_mfma_f32_16x16x32_bf16 v[74:77], v[156:159], v[226:229], v[74:77]
	s_setprio 0
	s_setprio 1
	v_mfma_f32_16x16x32_bf16 v[118:121], v[160:163], v[198:201], v[118:121]
	v_mfma_f32_16x16x32_bf16 v[114:117], v[168:171], v[198:201], v[114:117]
	v_mfma_f32_16x16x32_bf16 v[102:105], v[160:163], v[206:209], v[102:105]
	v_mfma_f32_16x16x32_bf16 v[98:101], v[168:171], v[206:209], v[98:101]
	v_mfma_f32_16x16x32_bf16 v[86:89], v[160:163], v[214:217], v[86:89]
	v_mfma_f32_16x16x32_bf16 v[82:85], v[168:171], v[214:217], v[82:85]
	v_mfma_f32_16x16x32_bf16 v[70:73], v[160:163], v[222:225], v[70:73]
	v_mfma_f32_16x16x32_bf16 v[66:69], v[168:171], v[222:225], v[66:69]
	v_mfma_f32_16x16x32_bf16 v[118:121], v[164:167], v[202:205], v[118:121]
	v_mfma_f32_16x16x32_bf16 v[114:117], v[194:197], v[202:205], v[114:117]
	v_mfma_f32_16x16x32_bf16 v[102:105], v[164:167], v[210:213], v[102:105]
	v_mfma_f32_16x16x32_bf16 v[98:101], v[194:197], v[210:213], v[98:101]
	v_mfma_f32_16x16x32_bf16 v[86:89], v[164:167], v[218:221], v[86:89]
	v_mfma_f32_16x16x32_bf16 v[82:85], v[194:197], v[218:221], v[82:85]
	v_mfma_f32_16x16x32_bf16 v[70:73], v[164:167], v[226:229], v[70:73]
	v_mfma_f32_16x16x32_bf16 v[66:69], v[194:197], v[226:229], v[66:69]
	s_setprio 0
	s_barrier
	s_add_i32 s47, s87, s24
	v_lshl_add_u64 v[230:231], s[2:3], 0, v[136:137]
	s_mov_b32 m0, s47
	ds_read_b128 v[198:201], v190 offset:16384
	ds_read_b128 v[202:205], v190 offset:17408
	ds_read_b128 v[206:209], v190 offset:18432
	ds_read_b128 v[210:213], v190 offset:19456
	ds_read_b128 v[214:217], v190 offset:20480
	ds_read_b128 v[218:221], v190 offset:21504
	ds_read_b128 v[222:225], v190 offset:22528
	ds_read_b128 v[226:229], v190 offset:23552
	global_load_lds_dwordx4 v[230:231], off
	s_add_i32 m0, s47, 0x2000
	s_add_u32 s48, s2, 0x100000
	v_lshl_add_u64 v[232:233], s[2:3], 0, v[140:141]
	s_addc_u32 s49, s3, 0
	s_add_i32 s47, s88, s24
	global_load_lds_dwordx4 v[232:233], off
	v_lshl_add_u64 v[234:235], s[48:49], 0, v[136:137]
	s_mov_b32 m0, s47
	v_lshl_add_u64 v[236:237], s[38:39], 0, v[138:139]
	global_load_lds_dwordx4 v[234:235], off
	v_lshl_add_u64 v[234:235], s[48:49], 0, v[140:141]
	s_add_i32 m0, s47, 0x2000
	s_nop 0
	global_load_lds_dwordx4 v[234:235], off
	v_lshl_add_u64 v[234:235], s[38:39], 0, v[134:135]
	s_mov_b32 m0, s25
	s_nop 0
	global_load_lds_dwordx4 v[234:235], off
	s_mov_b32 m0, s53
	s_nop 0
	global_load_lds_dwordx4 v[236:237], off
	s_waitcnt vmcnt(8)
	s_waitcnt lgkmcnt(0)
	s_setprio 1
	s_barrier
	v_mfma_f32_16x16x32_bf16 v[62:65], v[130:133], v[198:201], v[62:65]
	v_mfma_f32_16x16x32_bf16 v[58:61], v[152:155], v[198:201], v[58:61]
	v_mfma_f32_16x16x32_bf16 v[46:49], v[130:133], v[206:209], v[46:49]
	v_mfma_f32_16x16x32_bf16 v[42:45], v[152:155], v[206:209], v[42:45]
	v_mfma_f32_16x16x32_bf16 v[30:33], v[130:133], v[214:217], v[30:33]
	v_mfma_f32_16x16x32_bf16 v[26:29], v[152:155], v[214:217], v[26:29]
	v_mfma_f32_16x16x32_bf16 v[14:17], v[130:133], v[222:225], v[14:17]
	v_mfma_f32_16x16x32_bf16 v[10:13], v[152:155], v[222:225], v[10:13]
	v_mfma_f32_16x16x32_bf16 v[62:65], v[148:151], v[202:205], v[62:65]
	v_mfma_f32_16x16x32_bf16 v[58:61], v[156:159], v[202:205], v[58:61]
	v_mfma_f32_16x16x32_bf16 v[46:49], v[148:151], v[210:213], v[46:49]
	v_mfma_f32_16x16x32_bf16 v[42:45], v[156:159], v[210:213], v[42:45]
	v_mfma_f32_16x16x32_bf16 v[30:33], v[148:151], v[218:221], v[30:33]
	v_mfma_f32_16x16x32_bf16 v[26:29], v[156:159], v[218:221], v[26:29]
	v_mfma_f32_16x16x32_bf16 v[14:17], v[148:151], v[226:229], v[14:17]
	v_mfma_f32_16x16x32_bf16 v[10:13], v[156:159], v[226:229], v[10:13]
	s_setprio 0
	s_setprio 1
	v_mfma_f32_16x16x32_bf16 v[54:57], v[160:163], v[198:201], v[54:57]
	v_mfma_f32_16x16x32_bf16 v[50:53], v[168:171], v[198:201], v[50:53]
	v_mfma_f32_16x16x32_bf16 v[38:41], v[160:163], v[206:209], v[38:41]
	v_mfma_f32_16x16x32_bf16 v[34:37], v[168:171], v[206:209], v[34:37]
	v_mfma_f32_16x16x32_bf16 v[22:25], v[160:163], v[214:217], v[22:25]
	v_mfma_f32_16x16x32_bf16 v[18:21], v[168:171], v[214:217], v[18:21]
	v_mfma_f32_16x16x32_bf16 v[6:9], v[160:163], v[222:225], v[6:9]
	v_mfma_f32_16x16x32_bf16 v[2:5], v[168:171], v[222:225], v[2:5]
	v_mfma_f32_16x16x32_bf16 v[54:57], v[164:167], v[202:205], v[54:57]
	v_mfma_f32_16x16x32_bf16 v[50:53], v[194:197], v[202:205], v[50:53]
	v_mfma_f32_16x16x32_bf16 v[38:41], v[164:167], v[210:213], v[38:41]
	v_mfma_f32_16x16x32_bf16 v[34:37], v[194:197], v[210:213], v[34:37]
	v_mfma_f32_16x16x32_bf16 v[22:25], v[164:167], v[218:221], v[22:25]
	v_mfma_f32_16x16x32_bf16 v[18:21], v[194:197], v[218:221], v[18:21]
	v_mfma_f32_16x16x32_bf16 v[6:9], v[164:167], v[226:229], v[6:9]
	v_mfma_f32_16x16x32_bf16 v[2:5], v[194:197], v[226:229], v[2:5]
	s_setprio 0
	s_barrier
	s_add_i32 s47, 0, 0x18000
	v_add_u32_e32 v142, s47, v187
	s_add_i32 s48, 0, 0x1c000
	ds_read_b128 v[130:133], v142
	ds_read_b128 v[148:151], v142 offset:1024
	ds_read_b128 v[152:155], v142 offset:2048
	ds_read_b128 v[156:159], v142 offset:3072
	v_add_u32_e32 v142, s48, v187
	ds_read_b128 v[160:163], v142
	ds_read_b128 v[164:167], v142 offset:1024
	ds_read_b128 v[168:171], v142 offset:2048
	ds_read_b128 v[194:197], v142 offset:3072
	s_add_u32 s38, s38, 0x100000
	s_addc_u32 s39, s39, 0
	s_mov_b32 m0, s68
	v_lshl_add_u64 v[238:239], s[38:39], 0, v[134:135]
	ds_read_b128 v[198:201], v190 offset:32768
	ds_read_b128 v[202:205], v190 offset:33792
	ds_read_b128 v[206:209], v190 offset:34816
	ds_read_b128 v[210:213], v190 offset:35840
	ds_read_b128 v[214:217], v190 offset:36864
	ds_read_b128 v[218:221], v190 offset:37888
	ds_read_b128 v[222:225], v190 offset:38912
	ds_read_b128 v[226:229], v190 offset:39936
	global_load_lds_dwordx4 v[238:239], off
	v_lshl_add_u64 v[238:239], s[38:39], 0, v[138:139]
	s_mov_b32 m0, s72
	s_nop 0
	global_load_lds_dwordx4 v[238:239], off
	s_waitcnt vmcnt(8)
	s_waitcnt lgkmcnt(0)
	s_setprio 1
	s_barrier
	v_mfma_f32_16x16x32_bf16 v[126:129], v[130:133], v[198:201], v[126:129]
	v_mfma_f32_16x16x32_bf16 v[122:125], v[152:155], v[198:201], v[122:125]
	v_mfma_f32_16x16x32_bf16 v[110:113], v[130:133], v[206:209], v[110:113]
	v_mfma_f32_16x16x32_bf16 v[106:109], v[152:155], v[206:209], v[106:109]
	v_mfma_f32_16x16x32_bf16 v[94:97], v[130:133], v[214:217], v[94:97]
	v_mfma_f32_16x16x32_bf16 v[90:93], v[152:155], v[214:217], v[90:93]
	v_mfma_f32_16x16x32_bf16 v[78:81], v[130:133], v[222:225], v[78:81]
	v_mfma_f32_16x16x32_bf16 v[74:77], v[152:155], v[222:225], v[74:77]
	v_mfma_f32_16x16x32_bf16 v[126:129], v[148:151], v[202:205], v[126:129]
	v_mfma_f32_16x16x32_bf16 v[122:125], v[156:159], v[202:205], v[122:125]
	v_mfma_f32_16x16x32_bf16 v[110:113], v[148:151], v[210:213], v[110:113]
	v_mfma_f32_16x16x32_bf16 v[106:109], v[156:159], v[210:213], v[106:109]
	v_mfma_f32_16x16x32_bf16 v[94:97], v[148:151], v[218:221], v[94:97]
	v_mfma_f32_16x16x32_bf16 v[90:93], v[156:159], v[218:221], v[90:93]
	v_mfma_f32_16x16x32_bf16 v[78:81], v[148:151], v[226:229], v[78:81]
	v_mfma_f32_16x16x32_bf16 v[74:77], v[156:159], v[226:229], v[74:77]
	s_setprio 0
	s_setprio 1
	v_mfma_f32_16x16x32_bf16 v[118:121], v[160:163], v[198:201], v[118:121]
	v_mfma_f32_16x16x32_bf16 v[114:117], v[168:171], v[198:201], v[114:117]
	v_mfma_f32_16x16x32_bf16 v[102:105], v[160:163], v[206:209], v[102:105]
	v_mfma_f32_16x16x32_bf16 v[98:101], v[168:171], v[206:209], v[98:101]
	v_mfma_f32_16x16x32_bf16 v[86:89], v[160:163], v[214:217], v[86:89]
	v_mfma_f32_16x16x32_bf16 v[82:85], v[168:171], v[214:217], v[82:85]
	v_mfma_f32_16x16x32_bf16 v[70:73], v[160:163], v[222:225], v[70:73]
	v_mfma_f32_16x16x32_bf16 v[66:69], v[168:171], v[222:225], v[66:69]
	v_mfma_f32_16x16x32_bf16 v[118:121], v[164:167], v[202:205], v[118:121]
	v_mfma_f32_16x16x32_bf16 v[114:117], v[194:197], v[202:205], v[114:117]
	v_mfma_f32_16x16x32_bf16 v[102:105], v[164:167], v[210:213], v[102:105]
	v_mfma_f32_16x16x32_bf16 v[98:101], v[194:197], v[210:213], v[98:101]
	v_mfma_f32_16x16x32_bf16 v[86:89], v[164:167], v[218:221], v[86:89]
	v_mfma_f32_16x16x32_bf16 v[82:85], v[194:197], v[218:221], v[82:85]
	v_mfma_f32_16x16x32_bf16 v[70:73], v[164:167], v[226:229], v[70:73]
	v_mfma_f32_16x16x32_bf16 v[66:69], v[194:197], v[226:229], v[66:69]
	s_setprio 0
	s_barrier
	s_add_i32 s38, s47, s24
	v_lshl_add_u64 v[230:231], v[230:231], 0, s[10:11]
	s_mov_b32 m0, s38
	ds_read_b128 v[198:201], v190 offset:49152
	ds_read_b128 v[202:205], v190 offset:50176
	ds_read_b128 v[206:209], v190 offset:51200
	ds_read_b128 v[210:213], v190 offset:52224
	ds_read_b128 v[214:217], v190 offset:53248
	ds_read_b128 v[218:221], v190 offset:54272
	ds_read_b128 v[222:225], v190 offset:55296
	ds_read_b128 v[226:229], v190 offset:56320
	global_load_lds_dwordx4 v[230:231], off
	s_add_i32 m0, s38, 0x2000
	s_add_u32 s2, s2, 0x100080
	v_lshl_add_u64 v[230:231], v[232:233], 0, s[10:11]
	s_addc_u32 s3, s3, 0
	s_add_i32 s38, s48, s24
	global_load_lds_dwordx4 v[230:231], off
	v_lshl_add_u64 v[230:231], s[2:3], 0, v[136:137]
	s_mov_b32 m0, s38
	s_nop 0
	global_load_lds_dwordx4 v[230:231], off
	v_lshl_add_u64 v[230:231], s[2:3], 0, v[140:141]
	s_add_i32 m0, s38, 0x2000
	s_nop 0
	global_load_lds_dwordx4 v[230:231], off
	v_lshl_add_u64 v[230:231], v[234:235], 0, s[10:11]
	s_mov_b32 m0, s77
	s_nop 0
	global_load_lds_dwordx4 v[230:231], off
	v_lshl_add_u64 v[230:231], v[236:237], 0, s[10:11]
	s_mov_b32 m0, s78
	s_nop 0
	global_load_lds_dwordx4 v[230:231], off
	s_waitcnt vmcnt(8)
	s_waitcnt lgkmcnt(0)
	s_setprio 1
	s_barrier
	v_mfma_f32_16x16x32_bf16 v[62:65], v[130:133], v[198:201], v[62:65]
	v_mfma_f32_16x16x32_bf16 v[58:61], v[152:155], v[198:201], v[58:61]
	v_mfma_f32_16x16x32_bf16 v[46:49], v[130:133], v[206:209], v[46:49]
	v_mfma_f32_16x16x32_bf16 v[42:45], v[152:155], v[206:209], v[42:45]
	v_mfma_f32_16x16x32_bf16 v[30:33], v[130:133], v[214:217], v[30:33]
	v_mfma_f32_16x16x32_bf16 v[26:29], v[152:155], v[214:217], v[26:29]
	v_mfma_f32_16x16x32_bf16 v[14:17], v[130:133], v[222:225], v[14:17]
	v_mfma_f32_16x16x32_bf16 v[10:13], v[152:155], v[222:225], v[10:13]
	v_mfma_f32_16x16x32_bf16 v[62:65], v[148:151], v[202:205], v[62:65]
	v_mfma_f32_16x16x32_bf16 v[58:61], v[156:159], v[202:205], v[58:61]
	v_mfma_f32_16x16x32_bf16 v[46:49], v[148:151], v[210:213], v[46:49]
	v_mfma_f32_16x16x32_bf16 v[42:45], v[156:159], v[210:213], v[42:45]
	v_mfma_f32_16x16x32_bf16 v[30:33], v[148:151], v[218:221], v[30:33]
	v_mfma_f32_16x16x32_bf16 v[26:29], v[156:159], v[218:221], v[26:29]
	v_mfma_f32_16x16x32_bf16 v[14:17], v[148:151], v[226:229], v[14:17]
	v_mfma_f32_16x16x32_bf16 v[10:13], v[156:159], v[226:229], v[10:13]
	s_setprio 0
	s_setprio 1
	v_mfma_f32_16x16x32_bf16 v[54:57], v[160:163], v[198:201], v[54:57]
	v_mfma_f32_16x16x32_bf16 v[50:53], v[168:171], v[198:201], v[50:53]
	v_mfma_f32_16x16x32_bf16 v[38:41], v[160:163], v[206:209], v[38:41]
	v_mfma_f32_16x16x32_bf16 v[34:37], v[168:171], v[206:209], v[34:37]
	v_mfma_f32_16x16x32_bf16 v[22:25], v[160:163], v[214:217], v[22:25]
	v_mfma_f32_16x16x32_bf16 v[18:21], v[168:171], v[214:217], v[18:21]
	v_mfma_f32_16x16x32_bf16 v[6:9], v[160:163], v[222:225], v[6:9]
	v_mfma_f32_16x16x32_bf16 v[2:5], v[168:171], v[222:225], v[2:5]
	v_mfma_f32_16x16x32_bf16 v[54:57], v[164:167], v[202:205], v[54:57]
	v_mfma_f32_16x16x32_bf16 v[50:53], v[194:197], v[202:205], v[50:53]
	v_mfma_f32_16x16x32_bf16 v[38:41], v[164:167], v[210:213], v[38:41]
	v_mfma_f32_16x16x32_bf16 v[34:37], v[194:197], v[210:213], v[34:37]
	v_mfma_f32_16x16x32_bf16 v[22:25], v[164:167], v[218:221], v[22:25]
	v_mfma_f32_16x16x32_bf16 v[18:21], v[194:197], v[218:221], v[18:21]
	v_mfma_f32_16x16x32_bf16 v[6:9], v[164:167], v[226:229], v[6:9]
	v_mfma_f32_16x16x32_bf16 v[2:5], v[194:197], v[226:229], v[2:5]
	s_setprio 0
	s_barrier
	s_add_i32 s43, s43, 2
	s_add_u32 s0, s0, 0x100
	s_addc_u32 s1, s1, 0
	s_add_u32 s33, s33, 0x100
	s_addc_u32 s42, s42, 0
	s_cmp_gt_u32 s43, 61
	s_cbranch_scc0 .LBB0_374
	s_and_b64 vcc, exec, s[12:13]
	s_cbranch_vccz .LBB0_377
	s_barrier

.LBB0_755:
	ds_read_b128 v[122:125], v175
	ds_read_b128 v[126:129], v175 offset:1024
	ds_read_b128 v[138:141], v175 offset:2048
	ds_read_b128 v[142:145], v175 offset:3072
	ds_read_b128 v[160:163], v176
	ds_read_b128 v[164:167], v176 offset:1024
	ds_read_b128 v[168:171], v176 offset:2048
	ds_read_b128 v[180:183], v176 offset:3072
	s_add_u32 s2, s0, 0xfff80080
	s_addc_u32 s3, s1, -1
	s_cmp_eq_u32 s35, 28
	s_cselect_b32 s39, s5, s3
	s_cselect_b32 s38, s6, s2
	s_cselect_b32 s3, s16, s33
	s_cselect_b32 s2, s17, s21
	v_lshl_add_u64 v[216:217], s[0:1], 0, v[156:157]
	s_add_i32 m0, s73, 0xc000
	ds_read_b128 v[184:187], v177
	ds_read_b128 v[188:191], v177 offset:1024
	ds_read_b128 v[192:195], v177 offset:2048
	ds_read_b128 v[196:199], v177 offset:3072
	ds_read_b128 v[200:203], v177 offset:4096
	ds_read_b128 v[204:207], v177 offset:5120
	ds_read_b128 v[208:211], v177 offset:6144
	ds_read_b128 v[212:215], v177 offset:7168
	global_load_lds_dwordx4 v[216:217], off
	v_lshl_add_u64 v[216:217], s[0:1], 0, v[158:159]
	s_add_i32 m0, s73, 0xe000
	s_nop 0
	global_load_lds_dwordx4 v[216:217], off
	s_waitcnt vmcnt(8)
	s_waitcnt lgkmcnt(0)
	s_setprio 1
	s_barrier
	v_mfma_i32_16x16x64_i8 v[118:121], v[122:125], v[184:187], v[118:121]
	v_mfma_i32_16x16x64_i8 v[114:117], v[138:141], v[184:187], v[114:117]
	v_mfma_i32_16x16x64_i8 v[102:105], v[122:125], v[192:195], v[102:105]
	v_mfma_i32_16x16x64_i8 v[98:101], v[138:141], v[192:195], v[98:101]
	v_mfma_i32_16x16x64_i8 v[94:97], v[122:125], v[200:203], v[94:97]
	v_mfma_i32_16x16x64_i8 v[86:89], v[138:141], v[200:203], v[86:89]
	v_mfma_i32_16x16x64_i8 v[78:81], v[122:125], v[208:211], v[78:81]
	v_mfma_i32_16x16x64_i8 v[70:73], v[138:141], v[208:211], v[70:73]
	v_mfma_i32_16x16x64_i8 v[118:121], v[126:129], v[188:191], v[118:121]
	v_mfma_i32_16x16x64_i8 v[114:117], v[142:145], v[188:191], v[114:117]
	v_mfma_i32_16x16x64_i8 v[102:105], v[126:129], v[196:199], v[102:105]
	v_mfma_i32_16x16x64_i8 v[98:101], v[142:145], v[196:199], v[98:101]
	v_mfma_i32_16x16x64_i8 v[94:97], v[126:129], v[204:207], v[94:97]
	v_mfma_i32_16x16x64_i8 v[86:89], v[142:145], v[204:207], v[86:89]
	v_mfma_i32_16x16x64_i8 v[78:81], v[126:129], v[212:215], v[78:81]
	v_mfma_i32_16x16x64_i8 v[70:73], v[142:145], v[212:215], v[70:73]
	s_setprio 0
	s_setprio 1
	v_mfma_i32_16x16x64_i8 v[110:113], v[160:163], v[184:187], v[110:113]
	v_mfma_i32_16x16x64_i8 v[106:109], v[168:171], v[184:187], v[106:109]
	v_mfma_i32_16x16x64_i8 v[90:93], v[160:163], v[192:195], v[90:93]
	v_mfma_i32_16x16x64_i8 v[82:85], v[168:171], v[192:195], v[82:85]
	v_mfma_i32_16x16x64_i8 v[74:77], v[160:163], v[200:203], v[74:77]
	v_mfma_i32_16x16x64_i8 v[66:69], v[168:171], v[200:203], v[66:69]
	v_mfma_i32_16x16x64_i8 v[62:65], v[160:163], v[208:211], v[62:65]
	v_mfma_i32_16x16x64_i8 v[58:61], v[168:171], v[208:211], v[58:61]
	v_mfma_i32_16x16x64_i8 v[110:113], v[164:167], v[188:191], v[110:113]
	v_mfma_i32_16x16x64_i8 v[106:109], v[180:183], v[188:191], v[106:109]
	v_mfma_i32_16x16x64_i8 v[90:93], v[164:167], v[196:199], v[90:93]
	v_mfma_i32_16x16x64_i8 v[82:85], v[180:183], v[196:199], v[82:85]
	v_mfma_i32_16x16x64_i8 v[74:77], v[164:167], v[204:207], v[74:77]
	v_mfma_i32_16x16x64_i8 v[66:69], v[180:183], v[204:207], v[66:69]
	v_mfma_i32_16x16x64_i8 v[62:65], v[164:167], v[212:215], v[62:65]
	v_mfma_i32_16x16x64_i8 v[58:61], v[180:183], v[212:215], v[58:61]
	s_setprio 0
	s_barrier
	s_add_i32 s42, s24, s72
	v_lshl_add_u64 v[216:217], s[2:3], 0, v[148:149]
	s_mov_b32 m0, s42
	ds_read_b128 v[184:187], v177 offset:16384
	ds_read_b128 v[188:191], v177 offset:17408
	ds_read_b128 v[192:195], v177 offset:18432
	ds_read_b128 v[196:199], v177 offset:19456
	ds_read_b128 v[200:203], v177 offset:20480
	ds_read_b128 v[204:207], v177 offset:21504
	ds_read_b128 v[208:211], v177 offset:22528
	ds_read_b128 v[212:215], v177 offset:23552
	global_load_lds_dwordx4 v[216:217], off
	s_add_i32 m0, s42, 0x2000
	s_add_u32 s42, s2, 0x80000
	v_lshl_add_u64 v[218:219], s[2:3], 0, v[152:153]
	s_addc_u32 s43, s3, 0
	s_add_i32 s49, s25, s72
	global_load_lds_dwordx4 v[218:219], off
	v_lshl_add_u64 v[220:221], s[42:43], 0, v[148:149]
	s_mov_b32 m0, s49
	v_lshl_add_u64 v[222:223], s[38:39], 0, v[150:151]
	global_load_lds_dwordx4 v[220:221], off
	v_lshl_add_u64 v[220:221], s[42:43], 0, v[152:153]
	s_add_i32 m0, s49, 0x2000
	s_nop 0
	global_load_lds_dwordx4 v[220:221], off
	v_lshl_add_u64 v[220:221], s[38:39], 0, v[146:147]
	s_mov_b32 m0, s73
	s_nop 0
	global_load_lds_dwordx4 v[220:221], off
	s_mov_b32 m0, s74
	s_nop 0
	global_load_lds_dwordx4 v[222:223], off
	s_waitcnt vmcnt(8)
	s_waitcnt lgkmcnt(0)
	s_setprio 1
	s_barrier
	v_mfma_i32_16x16x64_i8 v[54:57], v[122:125], v[184:187], v[54:57]
	v_mfma_i32_16x16x64_i8 v[50:53], v[138:141], v[184:187], v[50:53]
	v_mfma_i32_16x16x64_i8 v[46:49], v[122:125], v[192:195], v[46:49]
	v_mfma_i32_16x16x64_i8 v[38:41], v[138:141], v[192:195], v[38:41]
	v_mfma_i32_16x16x64_i8 v[134:137], v[122:125], v[200:203], v[134:137]
	v_mfma_i32_16x16x64_i8 v[26:29], v[138:141], v[200:203], v[26:29]
	v_mfma_i32_16x16x64_i8 v[14:17], v[138:141], v[208:211], v[14:17]
	v_mfma_i32_16x16x64_i8 v[122:125], v[122:125], v[208:211], v[130:133]
	v_mfma_i32_16x16x64_i8 v[54:57], v[126:129], v[188:191], v[54:57]
	v_mfma_i32_16x16x64_i8 v[50:53], v[142:145], v[188:191], v[50:53]
	v_mfma_i32_16x16x64_i8 v[46:49], v[126:129], v[196:199], v[46:49]
	v_mfma_i32_16x16x64_i8 v[38:41], v[142:145], v[196:199], v[38:41]
	v_mfma_i32_16x16x64_i8 v[130:133], v[126:129], v[204:207], v[134:137]
	v_mfma_i32_16x16x64_i8 v[26:29], v[142:145], v[204:207], v[26:29]
	v_mfma_i32_16x16x64_i8 v[14:17], v[142:145], v[212:215], v[14:17]
	v_mfma_i32_16x16x64_i8 v[122:125], v[126:129], v[212:215], v[122:125]
	s_setprio 0
	s_setprio 1
	v_mfma_i32_16x16x64_i8 v[42:45], v[160:163], v[184:187], v[42:45]
	v_mfma_i32_16x16x64_i8 v[34:37], v[168:171], v[184:187], v[34:37]
	v_mfma_i32_16x16x64_i8 v[30:33], v[160:163], v[192:195], v[30:33]
	v_mfma_i32_16x16x64_i8 v[22:25], v[168:171], v[192:195], v[22:25]
	v_mfma_i32_16x16x64_i8 v[18:21], v[160:163], v[200:203], v[18:21]
	v_mfma_i32_16x16x64_i8 v[10:13], v[168:171], v[200:203], v[10:13]
	v_mfma_i32_16x16x64_i8 v[2:5], v[160:163], v[208:211], v[2:5]
	v_mfma_i32_16x16x64_i8 v[6:9], v[168:171], v[208:211], v[6:9]
	v_mfma_i32_16x16x64_i8 v[42:45], v[164:167], v[188:191], v[42:45]
	v_mfma_i32_16x16x64_i8 v[34:37], v[180:183], v[188:191], v[34:37]
	v_mfma_i32_16x16x64_i8 v[30:33], v[164:167], v[196:199], v[30:33]
	v_mfma_i32_16x16x64_i8 v[22:25], v[180:183], v[196:199], v[22:25]
	v_mfma_i32_16x16x64_i8 v[18:21], v[164:167], v[204:207], v[18:21]
	v_mfma_i32_16x16x64_i8 v[10:13], v[180:183], v[204:207], v[10:13]
	v_mfma_i32_16x16x64_i8 v[2:5], v[164:167], v[212:215], v[2:5]
	v_mfma_i32_16x16x64_i8 v[6:9], v[180:183], v[212:215], v[6:9]
	s_setprio 0
	s_barrier
	s_add_i32 s42, 0, 0x18000
	s_add_i32 s43, 0, 0x1c000
	v_add_u32_e32 v142, s42, v174
	v_add_u32_e32 v154, s43, v174
	ds_read_b128 v[126:129], v142
	ds_read_b128 v[138:141], v142 offset:1024
	ds_read_b128 v[134:137], v142 offset:2048
	ds_read_b128 v[142:145], v142 offset:3072
	ds_read_b128 v[160:163], v154
	ds_read_b128 v[164:167], v154 offset:1024
	ds_read_b128 v[168:171], v154 offset:2048
	ds_read_b128 v[180:183], v154 offset:3072
	s_add_u32 s38, s38, 0x80000
	s_addc_u32 s39, s39, 0
	s_mov_b32 m0, s75
	v_lshl_add_u64 v[224:225], s[38:39], 0, v[146:147]
	ds_read_b128 v[184:187], v177 offset:32768
	ds_read_b128 v[188:191], v177 offset:33792
	ds_read_b128 v[192:195], v177 offset:34816
	ds_read_b128 v[196:199], v177 offset:35840
	ds_read_b128 v[200:203], v177 offset:36864
	ds_read_b128 v[204:207], v177 offset:37888
	ds_read_b128 v[208:211], v177 offset:38912
	ds_read_b128 v[212:215], v177 offset:39936
	global_load_lds_dwordx4 v[224:225], off
	v_lshl_add_u64 v[224:225], s[38:39], 0, v[150:151]
	s_mov_b32 m0, s76
	s_nop 0
	global_load_lds_dwordx4 v[224:225], off
	s_waitcnt vmcnt(8)
	s_waitcnt lgkmcnt(0)
	s_setprio 1
	s_barrier
	v_mfma_i32_16x16x64_i8 v[118:121], v[126:129], v[184:187], v[118:121]
	v_mfma_i32_16x16x64_i8 v[114:117], v[134:137], v[184:187], v[114:117]
	v_mfma_i32_16x16x64_i8 v[102:105], v[126:129], v[192:195], v[102:105]
	v_mfma_i32_16x16x64_i8 v[98:101], v[134:137], v[192:195], v[98:101]
	v_mfma_i32_16x16x64_i8 v[94:97], v[126:129], v[200:203], v[94:97]
	v_mfma_i32_16x16x64_i8 v[86:89], v[134:137], v[200:203], v[86:89]
	v_mfma_i32_16x16x64_i8 v[78:81], v[126:129], v[208:211], v[78:81]
	v_mfma_i32_16x16x64_i8 v[70:73], v[134:137], v[208:211], v[70:73]
	v_mfma_i32_16x16x64_i8 v[118:121], v[138:141], v[188:191], v[118:121]
	v_mfma_i32_16x16x64_i8 v[114:117], v[142:145], v[188:191], v[114:117]
	v_mfma_i32_16x16x64_i8 v[102:105], v[138:141], v[196:199], v[102:105]
	v_mfma_i32_16x16x64_i8 v[98:101], v[142:145], v[196:199], v[98:101]
	v_mfma_i32_16x16x64_i8 v[94:97], v[138:141], v[204:207], v[94:97]
	v_mfma_i32_16x16x64_i8 v[86:89], v[142:145], v[204:207], v[86:89]
	v_mfma_i32_16x16x64_i8 v[78:81], v[138:141], v[212:215], v[78:81]
	v_mfma_i32_16x16x64_i8 v[70:73], v[142:145], v[212:215], v[70:73]
	s_setprio 0
	s_setprio 1
	v_mfma_i32_16x16x64_i8 v[110:113], v[160:163], v[184:187], v[110:113]
	v_mfma_i32_16x16x64_i8 v[106:109], v[168:171], v[184:187], v[106:109]
	v_mfma_i32_16x16x64_i8 v[90:93], v[160:163], v[192:195], v[90:93]
	v_mfma_i32_16x16x64_i8 v[82:85], v[168:171], v[192:195], v[82:85]
	v_mfma_i32_16x16x64_i8 v[74:77], v[160:163], v[200:203], v[74:77]
	v_mfma_i32_16x16x64_i8 v[66:69], v[168:171], v[200:203], v[66:69]
	v_mfma_i32_16x16x64_i8 v[62:65], v[160:163], v[208:211], v[62:65]
	v_mfma_i32_16x16x64_i8 v[58:61], v[168:171], v[208:211], v[58:61]
	v_mfma_i32_16x16x64_i8 v[110:113], v[164:167], v[188:191], v[110:113]
	v_mfma_i32_16x16x64_i8 v[106:109], v[180:183], v[188:191], v[106:109]
	v_mfma_i32_16x16x64_i8 v[90:93], v[164:167], v[196:199], v[90:93]
	v_mfma_i32_16x16x64_i8 v[82:85], v[180:183], v[196:199], v[82:85]
	v_mfma_i32_16x16x64_i8 v[74:77], v[164:167], v[204:207], v[74:77]
	v_mfma_i32_16x16x64_i8 v[66:69], v[180:183], v[204:207], v[66:69]
	v_mfma_i32_16x16x64_i8 v[62:65], v[164:167], v[212:215], v[62:65]
	v_mfma_i32_16x16x64_i8 v[58:61], v[180:183], v[212:215], v[58:61]
	s_setprio 0
	s_barrier
	s_add_i32 s38, s42, s72
	v_lshl_add_u64 v[216:217], v[216:217], 0, s[10:11]
	s_mov_b32 m0, s38
	ds_read_b128 v[184:187], v177 offset:49152
	ds_read_b128 v[188:191], v177 offset:50176
	ds_read_b128 v[192:195], v177 offset:51200
	ds_read_b128 v[196:199], v177 offset:52224
	ds_read_b128 v[200:203], v177 offset:53248
	ds_read_b128 v[204:207], v177 offset:54272
	ds_read_b128 v[208:211], v177 offset:55296
	ds_read_b128 v[212:215], v177 offset:56320
	global_load_lds_dwordx4 v[216:217], off
	s_add_i32 m0, s38, 0x2000
	s_add_u32 s2, s2, 0x80080
	v_lshl_add_u64 v[216:217], v[218:219], 0, s[10:11]
	s_addc_u32 s3, s3, 0
	s_add_i32 s38, s43, s72
	global_load_lds_dwordx4 v[216:217], off
	v_lshl_add_u64 v[216:217], s[2:3], 0, v[148:149]
	s_mov_b32 m0, s38
	s_nop 0
	global_load_lds_dwordx4 v[216:217], off
	v_lshl_add_u64 v[216:217], s[2:3], 0, v[152:153]
	s_add_i32 m0, s38, 0x2000
	s_nop 0
	global_load_lds_dwordx4 v[216:217], off
	v_lshl_add_u64 v[216:217], v[220:221], 0, s[10:11]
	s_mov_b32 m0, s82
	s_nop 0
	global_load_lds_dwordx4 v[216:217], off
	v_lshl_add_u64 v[216:217], v[222:223], 0, s[10:11]
	s_mov_b32 m0, s83
	s_nop 0
	global_load_lds_dwordx4 v[216:217], off
	s_waitcnt vmcnt(8)
	s_waitcnt lgkmcnt(0)
	s_setprio 1
	s_barrier
	v_mfma_i32_16x16x64_i8 v[54:57], v[126:129], v[184:187], v[54:57]
	v_mfma_i32_16x16x64_i8 v[50:53], v[134:137], v[184:187], v[50:53]
	v_mfma_i32_16x16x64_i8 v[46:49], v[126:129], v[192:195], v[46:49]
	v_mfma_i32_16x16x64_i8 v[38:41], v[134:137], v[192:195], v[38:41]
	v_mfma_i32_16x16x64_i8 v[130:133], v[126:129], v[200:203], v[130:133]
	v_mfma_i32_16x16x64_i8 v[26:29], v[134:137], v[200:203], v[26:29]
	v_mfma_i32_16x16x64_i8 v[122:125], v[126:129], v[208:211], v[122:125]
	v_mfma_i32_16x16x64_i8 v[14:17], v[134:137], v[208:211], v[14:17]
	v_mfma_i32_16x16x64_i8 v[54:57], v[138:141], v[188:191], v[54:57]
	v_mfma_i32_16x16x64_i8 v[50:53], v[142:145], v[188:191], v[50:53]
	v_mfma_i32_16x16x64_i8 v[46:49], v[138:141], v[196:199], v[46:49]
	v_mfma_i32_16x16x64_i8 v[38:41], v[142:145], v[196:199], v[38:41]
	v_mfma_i32_16x16x64_i8 v[134:137], v[138:141], v[204:207], v[130:133]
	v_mfma_i32_16x16x64_i8 v[26:29], v[142:145], v[204:207], v[26:29]
	v_mfma_i32_16x16x64_i8 v[130:133], v[138:141], v[212:215], v[122:125]
	v_mfma_i32_16x16x64_i8 v[14:17], v[142:145], v[212:215], v[14:17]
	s_setprio 0
	s_setprio 1
	v_mfma_i32_16x16x64_i8 v[42:45], v[160:163], v[184:187], v[42:45]
	v_mfma_i32_16x16x64_i8 v[34:37], v[168:171], v[184:187], v[34:37]
	v_mfma_i32_16x16x64_i8 v[30:33], v[160:163], v[192:195], v[30:33]
	v_mfma_i32_16x16x64_i8 v[22:25], v[168:171], v[192:195], v[22:25]
	v_mfma_i32_16x16x64_i8 v[18:21], v[160:163], v[200:203], v[18:21]
	v_mfma_i32_16x16x64_i8 v[10:13], v[168:171], v[200:203], v[10:13]
	v_mfma_i32_16x16x64_i8 v[2:5], v[160:163], v[208:211], v[2:5]
	v_mfma_i32_16x16x64_i8 v[6:9], v[168:171], v[208:211], v[6:9]
	v_mfma_i32_16x16x64_i8 v[42:45], v[164:167], v[188:191], v[42:45]
	v_mfma_i32_16x16x64_i8 v[34:37], v[180:183], v[188:191], v[34:37]
	v_mfma_i32_16x16x64_i8 v[30:33], v[164:167], v[196:199], v[30:33]
	v_mfma_i32_16x16x64_i8 v[22:25], v[180:183], v[196:199], v[22:25]
	v_mfma_i32_16x16x64_i8 v[18:21], v[164:167], v[204:207], v[18:21]
	v_mfma_i32_16x16x64_i8 v[10:13], v[180:183], v[204:207], v[10:13]
	v_mfma_i32_16x16x64_i8 v[2:5], v[164:167], v[212:215], v[2:5]
	v_mfma_i32_16x16x64_i8 v[6:9], v[180:183], v[212:215], v[6:9]
	s_setprio 0
	s_barrier
	s_add_i32 s35, s35, 2
	s_add_u32 s0, s0, 0x100
	s_addc_u32 s1, s1, 0
	s_add_u32 s21, s21, 0x100
	s_addc_u32 s33, s33, 0
	s_cmp_gt_u32 s35, 29
	s_cbranch_scc0 .LBB0_755
	s_and_b64 vcc, exec, s[12:13]
	s_cbranch_vccz .LBB0_758
	s_barrier

.LBB0_1493:
	ds_read_b128 v[26:29], v183
	ds_read_b128 v[30:33], v183 offset:1024
	ds_read_b128 v[18:21], v183 offset:2048
	ds_read_b128 v[22:25], v183 offset:3072
	ds_read_b128 v[10:13], v184
	ds_read_b128 v[14:17], v184 offset:1024
	ds_read_b128 v[2:5], v184 offset:2048
	ds_read_b128 v[6:9], v184 offset:3072
	s_add_i32 s55, s50, 2
	s_add_u32 s51, s48, 0xfff80080
	s_addc_u32 s52, s49, -1
	s_cmp_eq_u32 s39, s50
	s_cselect_b32 s50, s33, s43
	s_cselect_b32 s53, s27, s52
	s_cselect_b32 s52, s31, s51
	s_cselect_b32 s51, s29, s47
	v_lshl_add_u64 v[210:211], s[48:49], 0, v[166:167]
	s_add_i32 m0, s62, 0xc000
	ds_read_b128 v[172:175], v185
	ds_read_b128 v[176:179], v185 offset:1024
	ds_read_b128 v[186:189], v185 offset:2048
	ds_read_b128 v[190:193], v185 offset:3072
	ds_read_b128 v[194:197], v185 offset:4096
	ds_read_b128 v[198:201], v185 offset:5120
	ds_read_b128 v[202:205], v185 offset:6144
	ds_read_b128 v[206:209], v185 offset:7168
	global_load_lds_dwordx4 v[210:211], off
	v_lshl_add_u64 v[210:211], s[48:49], 0, v[168:169]
	s_add_i32 m0, s62, 0xe000
	s_nop 0
	global_load_lds_dwordx4 v[210:211], off
	s_waitcnt vmcnt(8)
	s_waitcnt lgkmcnt(0)
	s_setprio 1
	s_barrier
	v_mfma_f32_16x16x128_f8f6f4 v[158:161], v[26:33], v[172:179], v[158:161]
	v_mfma_f32_16x16x128_f8f6f4 v[154:157], v[18:25], v[172:179], v[154:157]
	v_mfma_f32_16x16x128_f8f6f4 v[150:153], v[26:33], v[186:193], v[150:153]
	v_mfma_f32_16x16x128_f8f6f4 v[146:149], v[18:25], v[186:193], v[146:149]
	v_mfma_f32_16x16x128_f8f6f4 v[126:129], v[26:33], v[194:201], v[126:129]
	v_mfma_f32_16x16x128_f8f6f4 v[122:125], v[18:25], v[194:201], v[122:125]
	v_mfma_f32_16x16x128_f8f6f4 v[114:117], v[26:33], v[202:209], v[114:117]
	v_mfma_f32_16x16x128_f8f6f4 v[106:109], v[18:25], v[202:209], v[106:109]
	s_setprio 0
	s_setprio 1
	v_mfma_f32_16x16x128_f8f6f4 v[142:145], v[10:17], v[172:179], v[142:145]
	v_mfma_f32_16x16x128_f8f6f4 v[138:141], v[2:9], v[172:179], v[138:141]
	v_mfma_f32_16x16x128_f8f6f4 v[134:137], v[10:17], v[186:193], v[134:137]
	v_mfma_f32_16x16x128_f8f6f4 v[130:133], v[2:9], v[186:193], v[130:133]
	v_mfma_f32_16x16x128_f8f6f4 v[118:121], v[10:17], v[194:201], v[118:121]
	v_mfma_f32_16x16x128_f8f6f4 v[110:113], v[2:9], v[194:201], v[110:113]
	v_mfma_f32_16x16x128_f8f6f4 v[102:105], v[10:17], v[202:209], v[102:105]
	v_mfma_f32_16x16x128_f8f6f4 v[98:101], v[2:9], v[202:209], v[98:101]
	s_setprio 0
	s_barrier
	s_add_i32 s79, s75, s61
	v_lshl_add_u64 v[172:173], s[50:51], 0, v[162:163]
	s_mov_b32 m0, s79
	ds_read_b128 v[186:189], v185 offset:16384
	ds_read_b128 v[190:193], v185 offset:17408
	ds_read_b128 v[194:197], v185 offset:18432
	ds_read_b128 v[198:201], v185 offset:19456
	ds_read_b128 v[202:205], v185 offset:20480
	ds_read_b128 v[206:209], v185 offset:21504
	ds_read_b128 v[210:213], v185 offset:22528
	ds_read_b128 v[214:217], v185 offset:23552
	global_load_lds_dwordx4 v[172:173], off
	s_add_i32 m0, s79, 0x2000
	s_add_u32 s82, s50, 0x80000
	v_lshl_add_u64 v[174:175], s[50:51], 0, v[164:165]
	s_addc_u32 s83, s51, 0
	s_add_i32 s79, s76, s61
	global_load_lds_dwordx4 v[174:175], off
	v_lshl_add_u64 v[176:177], s[82:83], 0, v[162:163]
	s_mov_b32 m0, s79
	v_lshl_add_u64 v[178:179], s[52:53], 0, v[164:165]
	global_load_lds_dwordx4 v[176:177], off
	v_lshl_add_u64 v[176:177], s[82:83], 0, v[164:165]
	s_add_i32 m0, s79, 0x2000
	s_nop 0
	global_load_lds_dwordx4 v[176:177], off
	v_lshl_add_u64 v[176:177], s[52:53], 0, v[162:163]
	s_mov_b32 m0, s62
	s_nop 0
	global_load_lds_dwordx4 v[176:177], off
	s_mov_b32 m0, s63
	s_nop 0
	global_load_lds_dwordx4 v[178:179], off
	s_waitcnt vmcnt(8)
	s_waitcnt lgkmcnt(0)
	s_setprio 1
	s_barrier
	v_mfma_f32_16x16x128_f8f6f4 v[94:97], v[26:33], v[186:193], v[94:97]
	v_mfma_f32_16x16x128_f8f6f4 v[90:93], v[18:25], v[186:193], v[90:93]
	v_mfma_f32_16x16x128_f8f6f4 v[82:85], v[26:33], v[194:201], v[82:85]
	v_mfma_f32_16x16x128_f8f6f4 v[74:77], v[18:25], v[194:201], v[74:77]
	v_mfma_f32_16x16x128_f8f6f4 v[66:69], v[26:33], v[202:209], v[66:69]
	v_mfma_f32_16x16x128_f8f6f4 v[58:61], v[18:25], v[202:209], v[58:61]
	v_mfma_f32_16x16x128_f8f6f4 v[50:53], v[26:33], v[210:217], v[50:53]
	v_mfma_f32_16x16x128_f8f6f4 v[42:45], v[18:25], v[210:217], v[42:45]
	s_setprio 0
	s_setprio 1
	v_mfma_f32_16x16x128_f8f6f4 v[86:89], v[10:17], v[186:193], v[86:89]
	v_mfma_f32_16x16x128_f8f6f4 v[78:81], v[2:9], v[186:193], v[78:81]
	v_mfma_f32_16x16x128_f8f6f4 v[70:73], v[10:17], v[194:201], v[70:73]
	v_mfma_f32_16x16x128_f8f6f4 v[62:65], v[2:9], v[194:201], v[62:65]
	v_mfma_f32_16x16x128_f8f6f4 v[54:57], v[10:17], v[202:209], v[54:57]
	v_mfma_f32_16x16x128_f8f6f4 v[46:49], v[2:9], v[202:209], v[46:49]
	v_mfma_f32_16x16x128_f8f6f4 v[38:41], v[10:17], v[210:217], v[38:41]
	v_mfma_f32_16x16x128_f8f6f4 v[34:37], v[2:9], v[210:217], v[34:37]
	s_setprio 0
	s_barrier
	s_add_i32 s79, 0, 0x18000
	s_add_i32 s82, 0, 0x1c000
	v_add_u32_e32 v14, s79, v182
	v_add_u32_e32 v30, s82, v182
	ds_read_b128 v[2:5], v14
	ds_read_b128 v[6:9], v14 offset:1024
	ds_read_b128 v[10:13], v14 offset:2048
	ds_read_b128 v[14:17], v14 offset:3072
	ds_read_b128 v[18:21], v30
	ds_read_b128 v[22:25], v30 offset:1024
	ds_read_b128 v[26:29], v30 offset:2048
	ds_read_b128 v[30:33], v30 offset:3072
	s_add_u32 s52, s52, 0x80000
	s_addc_u32 s53, s53, 0
	s_mov_b32 m0, s64
	v_lshl_add_u64 v[218:219], s[52:53], 0, v[162:163]
	ds_read_b128 v[186:189], v185 offset:32768
	ds_read_b128 v[190:193], v185 offset:33792
	ds_read_b128 v[194:197], v185 offset:34816
	ds_read_b128 v[198:201], v185 offset:35840
	ds_read_b128 v[202:205], v185 offset:36864
	ds_read_b128 v[206:209], v185 offset:37888
	ds_read_b128 v[210:213], v185 offset:38912
	ds_read_b128 v[214:217], v185 offset:39936
	global_load_lds_dwordx4 v[218:219], off
	v_lshl_add_u64 v[218:219], s[52:53], 0, v[164:165]
	s_mov_b32 m0, s65
	s_nop 0
	global_load_lds_dwordx4 v[218:219], off
	s_waitcnt vmcnt(8)
	s_waitcnt lgkmcnt(0)
	s_setprio 1
	s_barrier
	v_mfma_f32_16x16x128_f8f6f4 v[158:161], v[2:9], v[186:193], v[158:161]
	v_mfma_f32_16x16x128_f8f6f4 v[154:157], v[10:17], v[186:193], v[154:157]
	v_mfma_f32_16x16x128_f8f6f4 v[150:153], v[2:9], v[194:201], v[150:153]
	v_mfma_f32_16x16x128_f8f6f4 v[146:149], v[10:17], v[194:201], v[146:149]
	v_mfma_f32_16x16x128_f8f6f4 v[126:129], v[2:9], v[202:209], v[126:129]
	v_mfma_f32_16x16x128_f8f6f4 v[122:125], v[10:17], v[202:209], v[122:125]
	v_mfma_f32_16x16x128_f8f6f4 v[114:117], v[2:9], v[210:217], v[114:117]
	v_mfma_f32_16x16x128_f8f6f4 v[106:109], v[10:17], v[210:217], v[106:109]
	s_setprio 0
	s_setprio 1
	v_mfma_f32_16x16x128_f8f6f4 v[142:145], v[18:25], v[186:193], v[142:145]
	v_mfma_f32_16x16x128_f8f6f4 v[138:141], v[26:33], v[186:193], v[138:141]
	v_mfma_f32_16x16x128_f8f6f4 v[134:137], v[18:25], v[194:201], v[134:137]
	v_mfma_f32_16x16x128_f8f6f4 v[130:133], v[26:33], v[194:201], v[130:133]
	v_mfma_f32_16x16x128_f8f6f4 v[118:121], v[18:25], v[202:209], v[118:121]
	v_mfma_f32_16x16x128_f8f6f4 v[110:113], v[26:33], v[202:209], v[110:113]
	v_mfma_f32_16x16x128_f8f6f4 v[102:105], v[18:25], v[210:217], v[102:105]
	v_mfma_f32_16x16x128_f8f6f4 v[98:101], v[26:33], v[210:217], v[98:101]
	s_setprio 0
	s_barrier
	s_add_i32 s52, s79, s61
	v_lshl_add_u64 v[172:173], v[172:173], 0, s[12:13]
	s_mov_b32 m0, s52
	ds_read_b128 v[186:189], v185 offset:49152
	ds_read_b128 v[190:193], v185 offset:50176
	ds_read_b128 v[194:197], v185 offset:51200
	ds_read_b128 v[198:201], v185 offset:52224
	ds_read_b128 v[202:205], v185 offset:53248
	ds_read_b128 v[206:209], v185 offset:54272
	ds_read_b128 v[210:213], v185 offset:55296
	ds_read_b128 v[214:217], v185 offset:56320
	global_load_lds_dwordx4 v[172:173], off
	s_add_i32 m0, s52, 0x2000
	s_add_u32 s50, s50, 0x80080
	v_lshl_add_u64 v[172:173], v[174:175], 0, s[12:13]
	s_addc_u32 s51, s51, 0
	s_add_i32 s52, s82, s61
	global_load_lds_dwordx4 v[172:173], off
	v_lshl_add_u64 v[172:173], s[50:51], 0, v[162:163]
	s_mov_b32 m0, s52
	s_nop 0
	global_load_lds_dwordx4 v[172:173], off
	v_lshl_add_u64 v[172:173], s[50:51], 0, v[164:165]
	s_add_i32 m0, s52, 0x2000
	s_nop 0
	global_load_lds_dwordx4 v[172:173], off
	v_lshl_add_u64 v[172:173], v[176:177], 0, s[12:13]
	s_mov_b32 m0, s70
	s_nop 0
	global_load_lds_dwordx4 v[172:173], off
	v_lshl_add_u64 v[172:173], v[178:179], 0, s[12:13]
	s_mov_b32 m0, s71
	s_nop 0
	global_load_lds_dwordx4 v[172:173], off
	s_waitcnt vmcnt(8)
	s_waitcnt lgkmcnt(0)
	s_setprio 1
	s_barrier
	v_mfma_f32_16x16x128_f8f6f4 v[94:97], v[2:9], v[186:193], v[94:97]
	v_mfma_f32_16x16x128_f8f6f4 v[90:93], v[10:17], v[186:193], v[90:93]
	v_mfma_f32_16x16x128_f8f6f4 v[82:85], v[2:9], v[194:201], v[82:85]
	v_mfma_f32_16x16x128_f8f6f4 v[74:77], v[10:17], v[194:201], v[74:77]
	v_mfma_f32_16x16x128_f8f6f4 v[66:69], v[2:9], v[202:209], v[66:69]
	v_mfma_f32_16x16x128_f8f6f4 v[58:61], v[10:17], v[202:209], v[58:61]
	v_mfma_f32_16x16x128_f8f6f4 v[50:53], v[2:9], v[210:217], v[50:53]
	v_mfma_f32_16x16x128_f8f6f4 v[42:45], v[10:17], v[210:217], v[42:45]
	s_setprio 0
	s_setprio 1
	v_mfma_f32_16x16x128_f8f6f4 v[86:89], v[18:25], v[186:193], v[86:89]
	v_mfma_f32_16x16x128_f8f6f4 v[78:81], v[26:33], v[186:193], v[78:81]
	v_mfma_f32_16x16x128_f8f6f4 v[70:73], v[18:25], v[194:201], v[70:73]
	v_mfma_f32_16x16x128_f8f6f4 v[62:65], v[26:33], v[194:201], v[62:65]
	v_mfma_f32_16x16x128_f8f6f4 v[54:57], v[18:25], v[202:209], v[54:57]
	v_mfma_f32_16x16x128_f8f6f4 v[46:49], v[26:33], v[202:209], v[46:49]
	v_mfma_f32_16x16x128_f8f6f4 v[38:41], v[18:25], v[210:217], v[38:41]
	v_mfma_f32_16x16x128_f8f6f4 v[34:37], v[26:33], v[210:217], v[34:37]
	s_setprio 0
	s_barrier
	s_add_u32 s48, s48, 0x100
	s_addc_u32 s49, s49, 0
	s_add_u32 s43, s43, 0x100
	s_addc_u32 s47, s47, 0
	s_cmp_ge_i32 s55, s42
	s_mov_b32 s50, s55
	s_cbranch_scc0 .LBB0_1493
	s_and_b64 vcc, exec, s[14:15]
	s_cbranch_vccz .LBB0_1496
	s_barrier

.LBB0_1638:
	ds_read_b128 v[142:145], v160
	ds_read_b128 v[168:171], v160 offset:1024
	ds_read_b128 v[172:175], v160 offset:2048
	ds_read_b128 v[180:183], v160 offset:3072
	ds_read_b128 v[184:187], v161
	ds_read_b128 v[188:191], v161 offset:1024
	ds_read_b128 v[192:195], v161 offset:2048
	ds_read_b128 v[196:199], v161 offset:3072
	s_add_u32 s34, s30, 0xfff80080
	s_addc_u32 s35, s31, -1
	s_cmp_eq_u32 s70, 28
	s_cselect_b32 s39, s15, s35
	s_cselect_b32 s38, s27, s34
	s_cselect_b32 s35, s17, s69
	s_cselect_b32 s34, s33, s68
	v_lshl_add_u64 v[146:147], s[30:31], 0, v[138:139]
	s_add_i32 m0, s29, 0xc000
	ds_read_b128 v[200:203], v165
	ds_read_b128 v[204:207], v165 offset:1024
	ds_read_b128 v[208:211], v165 offset:2048
	ds_read_b128 v[212:215], v165 offset:3072
	ds_read_b128 v[216:219], v165 offset:4096
	ds_read_b128 v[220:223], v165 offset:5120
	ds_read_b128 v[224:227], v165 offset:6144
	ds_read_b128 v[228:231], v165 offset:7168
	global_load_lds_dwordx4 v[146:147], off
	v_lshl_add_u64 v[146:147], s[30:31], 0, v[140:141]
	s_add_i32 m0, s29, 0xe000
	s_nop 0
	global_load_lds_dwordx4 v[146:147], off
	s_waitcnt vmcnt(8)
	s_waitcnt lgkmcnt(0)
	s_setprio 1
	s_barrier
	v_mfma_i32_16x16x64_i8 v[126:129], v[142:145], v[200:203], v[126:129]
	v_mfma_i32_16x16x64_i8 v[118:121], v[172:175], v[200:203], v[118:121]
	v_mfma_i32_16x16x64_i8 v[110:113], v[142:145], v[208:211], v[110:113]
	v_mfma_i32_16x16x64_i8 v[102:105], v[172:175], v[208:211], v[102:105]
	v_mfma_i32_16x16x64_i8 v[94:97], v[142:145], v[216:219], v[94:97]
	v_mfma_i32_16x16x64_i8 v[86:89], v[172:175], v[216:219], v[86:89]
	v_mfma_i32_16x16x64_i8 v[78:81], v[142:145], v[224:227], v[78:81]
	v_mfma_i32_16x16x64_i8 v[70:73], v[172:175], v[224:227], v[70:73]
	v_mfma_i32_16x16x64_i8 v[126:129], v[168:171], v[204:207], v[126:129]
	v_mfma_i32_16x16x64_i8 v[118:121], v[180:183], v[204:207], v[118:121]
	v_mfma_i32_16x16x64_i8 v[110:113], v[168:171], v[212:215], v[110:113]
	v_mfma_i32_16x16x64_i8 v[102:105], v[180:183], v[212:215], v[102:105]
	v_mfma_i32_16x16x64_i8 v[94:97], v[168:171], v[220:223], v[94:97]
	v_mfma_i32_16x16x64_i8 v[86:89], v[180:183], v[220:223], v[86:89]
	v_mfma_i32_16x16x64_i8 v[78:81], v[168:171], v[228:231], v[78:81]
	v_mfma_i32_16x16x64_i8 v[70:73], v[180:183], v[228:231], v[70:73]
	s_setprio 0
	s_setprio 1
	v_mfma_i32_16x16x64_i8 v[122:125], v[184:187], v[200:203], v[122:125]
	v_mfma_i32_16x16x64_i8 v[114:117], v[192:195], v[200:203], v[114:117]
	v_mfma_i32_16x16x64_i8 v[106:109], v[184:187], v[208:211], v[106:109]
	v_mfma_i32_16x16x64_i8 v[98:101], v[192:195], v[208:211], v[98:101]
	v_mfma_i32_16x16x64_i8 v[90:93], v[184:187], v[216:219], v[90:93]
	v_mfma_i32_16x16x64_i8 v[82:85], v[192:195], v[216:219], v[82:85]
	v_mfma_i32_16x16x64_i8 v[74:77], v[184:187], v[224:227], v[74:77]
	v_mfma_i32_16x16x64_i8 v[66:69], v[192:195], v[224:227], v[66:69]
	v_mfma_i32_16x16x64_i8 v[122:125], v[188:191], v[204:207], v[122:125]
	v_mfma_i32_16x16x64_i8 v[114:117], v[196:199], v[204:207], v[114:117]
	v_mfma_i32_16x16x64_i8 v[106:109], v[188:191], v[212:215], v[106:109]
	v_mfma_i32_16x16x64_i8 v[98:101], v[196:199], v[212:215], v[98:101]
	v_mfma_i32_16x16x64_i8 v[90:93], v[188:191], v[220:223], v[90:93]
	v_mfma_i32_16x16x64_i8 v[82:85], v[196:199], v[220:223], v[82:85]
	v_mfma_i32_16x16x64_i8 v[74:77], v[188:191], v[228:231], v[74:77]
	v_mfma_i32_16x16x64_i8 v[66:69], v[196:199], v[228:231], v[66:69]
	s_setprio 0
	s_barrier
	s_add_i32 s71, s58, s45
	v_lshl_add_u64 v[146:147], s[34:35], 0, v[132:133]
	s_mov_b32 m0, s71
	ds_read_b128 v[200:203], v165 offset:16384
	ds_read_b128 v[204:207], v165 offset:17408
	ds_read_b128 v[208:211], v165 offset:18432
	ds_read_b128 v[212:215], v165 offset:19456
	ds_read_b128 v[216:219], v165 offset:20480
	ds_read_b128 v[220:223], v165 offset:21504
	ds_read_b128 v[224:227], v165 offset:22528
	ds_read_b128 v[228:231], v165 offset:23552
	global_load_lds_dwordx4 v[146:147], off
	s_add_i32 m0, s71, 0x2000
	s_add_u32 s72, s34, 0x80000
	v_lshl_add_u64 v[156:157], s[34:35], 0, v[136:137]
	s_addc_u32 s73, s35, 0
	s_add_i32 s71, s59, s45
	global_load_lds_dwordx4 v[156:157], off
	v_lshl_add_u64 v[176:177], s[72:73], 0, v[132:133]
	s_mov_b32 m0, s71
	v_lshl_add_u64 v[232:233], s[38:39], 0, v[134:135]
	global_load_lds_dwordx4 v[176:177], off
	v_lshl_add_u64 v[176:177], s[72:73], 0, v[136:137]
	s_add_i32 m0, s71, 0x2000
	s_nop 0
	global_load_lds_dwordx4 v[176:177], off
	v_lshl_add_u64 v[176:177], s[38:39], 0, v[130:131]
	s_mov_b32 m0, s29
	s_nop 0
	global_load_lds_dwordx4 v[176:177], off
	s_mov_b32 m0, s46
	s_nop 0
	global_load_lds_dwordx4 v[232:233], off
	s_waitcnt vmcnt(8)
	s_waitcnt lgkmcnt(0)
	s_setprio 1
	s_barrier
	v_mfma_i32_16x16x64_i8 v[62:65], v[142:145], v[200:203], v[62:65]
	v_mfma_i32_16x16x64_i8 v[54:57], v[172:175], v[200:203], v[54:57]
	v_mfma_i32_16x16x64_i8 v[46:49], v[142:145], v[208:211], v[46:49]
	v_mfma_i32_16x16x64_i8 v[38:41], v[172:175], v[208:211], v[38:41]
	v_mfma_i32_16x16x64_i8 v[30:33], v[142:145], v[216:219], v[30:33]
	v_mfma_i32_16x16x64_i8 v[22:25], v[172:175], v[216:219], v[22:25]
	v_mfma_i32_16x16x64_i8 v[14:17], v[142:145], v[224:227], v[14:17]
	v_mfma_i32_16x16x64_i8 v[6:9], v[172:175], v[224:227], v[6:9]
	v_mfma_i32_16x16x64_i8 v[62:65], v[168:171], v[204:207], v[62:65]
	v_mfma_i32_16x16x64_i8 v[54:57], v[180:183], v[204:207], v[54:57]
	v_mfma_i32_16x16x64_i8 v[46:49], v[168:171], v[212:215], v[46:49]
	v_mfma_i32_16x16x64_i8 v[38:41], v[180:183], v[212:215], v[38:41]
	v_mfma_i32_16x16x64_i8 v[30:33], v[168:171], v[220:223], v[30:33]
	v_mfma_i32_16x16x64_i8 v[22:25], v[180:183], v[220:223], v[22:25]
	v_mfma_i32_16x16x64_i8 v[14:17], v[168:171], v[228:231], v[14:17]
	v_mfma_i32_16x16x64_i8 v[6:9], v[180:183], v[228:231], v[6:9]
	s_setprio 0
	s_setprio 1
	v_mfma_i32_16x16x64_i8 v[58:61], v[184:187], v[200:203], v[58:61]
	v_mfma_i32_16x16x64_i8 v[50:53], v[192:195], v[200:203], v[50:53]
	v_mfma_i32_16x16x64_i8 v[42:45], v[184:187], v[208:211], v[42:45]
	v_mfma_i32_16x16x64_i8 v[34:37], v[192:195], v[208:211], v[34:37]
	v_mfma_i32_16x16x64_i8 v[26:29], v[184:187], v[216:219], v[26:29]
	v_mfma_i32_16x16x64_i8 v[18:21], v[192:195], v[216:219], v[18:21]
	v_mfma_i32_16x16x64_i8 v[10:13], v[184:187], v[224:227], v[10:13]
	v_mfma_i32_16x16x64_i8 v[2:5], v[192:195], v[224:227], v[2:5]
	v_mfma_i32_16x16x64_i8 v[58:61], v[188:191], v[204:207], v[58:61]
	v_mfma_i32_16x16x64_i8 v[50:53], v[196:199], v[204:207], v[50:53]
	v_mfma_i32_16x16x64_i8 v[42:45], v[188:191], v[212:215], v[42:45]
	v_mfma_i32_16x16x64_i8 v[34:37], v[196:199], v[212:215], v[34:37]
	v_mfma_i32_16x16x64_i8 v[26:29], v[188:191], v[220:223], v[26:29]
	v_mfma_i32_16x16x64_i8 v[18:21], v[196:199], v[220:223], v[18:21]
	v_mfma_i32_16x16x64_i8 v[10:13], v[188:191], v[228:231], v[10:13]
	v_mfma_i32_16x16x64_i8 v[2:5], v[196:199], v[228:231], v[2:5]
	s_setprio 0
	s_barrier
	s_add_i32 s71, 0, 0x18000
	v_add_u32_e32 v148, s71, v158
	s_add_i32 s72, 0, 0x1c000
	ds_read_b128 v[142:145], v148
	ds_read_b128 v[168:171], v148 offset:1024
	ds_read_b128 v[172:175], v148 offset:2048
	ds_read_b128 v[180:183], v148 offset:3072
	v_add_u32_e32 v148, s72, v158
	ds_read_b128 v[184:187], v148
	ds_read_b128 v[188:191], v148 offset:1024
	ds_read_b128 v[192:195], v148 offset:2048
	ds_read_b128 v[196:199], v148 offset:3072
	s_add_u32 s38, s38, 0x80000
	s_addc_u32 s39, s39, 0
	s_mov_b32 m0, s47
	v_lshl_add_u64 v[234:235], s[38:39], 0, v[130:131]
	ds_read_b128 v[200:203], v165 offset:32768
	ds_read_b128 v[204:207], v165 offset:33792
	ds_read_b128 v[208:211], v165 offset:34816
	ds_read_b128 v[212:215], v165 offset:35840
	ds_read_b128 v[216:219], v165 offset:36864
	ds_read_b128 v[220:223], v165 offset:37888
	ds_read_b128 v[224:227], v165 offset:38912
	ds_read_b128 v[228:231], v165 offset:39936
	global_load_lds_dwordx4 v[234:235], off
	v_lshl_add_u64 v[234:235], s[38:39], 0, v[134:135]
	s_mov_b32 m0, s48
	s_nop 0
	global_load_lds_dwordx4 v[234:235], off
	s_waitcnt vmcnt(8)
	s_waitcnt lgkmcnt(0)
	s_setprio 1
	s_barrier
	v_mfma_i32_16x16x64_i8 v[126:129], v[142:145], v[200:203], v[126:129]
	v_mfma_i32_16x16x64_i8 v[118:121], v[172:175], v[200:203], v[118:121]
	v_mfma_i32_16x16x64_i8 v[110:113], v[142:145], v[208:211], v[110:113]
	v_mfma_i32_16x16x64_i8 v[102:105], v[172:175], v[208:211], v[102:105]
	v_mfma_i32_16x16x64_i8 v[94:97], v[142:145], v[216:219], v[94:97]
	v_mfma_i32_16x16x64_i8 v[86:89], v[172:175], v[216:219], v[86:89]
	v_mfma_i32_16x16x64_i8 v[78:81], v[142:145], v[224:227], v[78:81]
	v_mfma_i32_16x16x64_i8 v[70:73], v[172:175], v[224:227], v[70:73]
	v_mfma_i32_16x16x64_i8 v[126:129], v[168:171], v[204:207], v[126:129]
	v_mfma_i32_16x16x64_i8 v[118:121], v[180:183], v[204:207], v[118:121]
	v_mfma_i32_16x16x64_i8 v[110:113], v[168:171], v[212:215], v[110:113]
	v_mfma_i32_16x16x64_i8 v[102:105], v[180:183], v[212:215], v[102:105]
	v_mfma_i32_16x16x64_i8 v[94:97], v[168:171], v[220:223], v[94:97]
	v_mfma_i32_16x16x64_i8 v[86:89], v[180:183], v[220:223], v[86:89]
	v_mfma_i32_16x16x64_i8 v[78:81], v[168:171], v[228:231], v[78:81]
	v_mfma_i32_16x16x64_i8 v[70:73], v[180:183], v[228:231], v[70:73]
	s_setprio 0
	s_setprio 1
	v_mfma_i32_16x16x64_i8 v[122:125], v[184:187], v[200:203], v[122:125]
	v_mfma_i32_16x16x64_i8 v[114:117], v[192:195], v[200:203], v[114:117]
	v_mfma_i32_16x16x64_i8 v[106:109], v[184:187], v[208:211], v[106:109]
	v_mfma_i32_16x16x64_i8 v[98:101], v[192:195], v[208:211], v[98:101]
	v_mfma_i32_16x16x64_i8 v[90:93], v[184:187], v[216:219], v[90:93]
	v_mfma_i32_16x16x64_i8 v[82:85], v[192:195], v[216:219], v[82:85]
	v_mfma_i32_16x16x64_i8 v[74:77], v[184:187], v[224:227], v[74:77]
	v_mfma_i32_16x16x64_i8 v[66:69], v[192:195], v[224:227], v[66:69]
	v_mfma_i32_16x16x64_i8 v[122:125], v[188:191], v[204:207], v[122:125]
	v_mfma_i32_16x16x64_i8 v[114:117], v[196:199], v[204:207], v[114:117]
	v_mfma_i32_16x16x64_i8 v[106:109], v[188:191], v[212:215], v[106:109]
	v_mfma_i32_16x16x64_i8 v[98:101], v[196:199], v[212:215], v[98:101]
	v_mfma_i32_16x16x64_i8 v[90:93], v[188:191], v[220:223], v[90:93]
	v_mfma_i32_16x16x64_i8 v[82:85], v[196:199], v[220:223], v[82:85]
	v_mfma_i32_16x16x64_i8 v[74:77], v[188:191], v[228:231], v[74:77]
	v_mfma_i32_16x16x64_i8 v[66:69], v[196:199], v[228:231], v[66:69]
	s_setprio 0
	s_barrier
	s_add_i32 s38, s71, s45
	v_lshl_add_u64 v[146:147], v[146:147], 0, s[8:9]
	s_mov_b32 m0, s38
	ds_read_b128 v[200:203], v165 offset:49152
	ds_read_b128 v[204:207], v165 offset:50176
	ds_read_b128 v[208:211], v165 offset:51200
	ds_read_b128 v[212:215], v165 offset:52224
	ds_read_b128 v[216:219], v165 offset:53248
	ds_read_b128 v[220:223], v165 offset:54272
	ds_read_b128 v[224:227], v165 offset:55296
	ds_read_b128 v[228:231], v165 offset:56320
	global_load_lds_dwordx4 v[146:147], off
	s_add_i32 m0, s38, 0x2000
	s_add_u32 s34, s34, 0x80080
	v_lshl_add_u64 v[146:147], v[156:157], 0, s[8:9]
	s_addc_u32 s35, s35, 0
	s_add_i32 s38, s72, s45
	global_load_lds_dwordx4 v[146:147], off
	v_lshl_add_u64 v[146:147], s[34:35], 0, v[132:133]
	s_mov_b32 m0, s38
	s_nop 0
	global_load_lds_dwordx4 v[146:147], off
	v_lshl_add_u64 v[146:147], s[34:35], 0, v[136:137]
	s_add_i32 m0, s38, 0x2000
	s_nop 0
	global_load_lds_dwordx4 v[146:147], off
	v_lshl_add_u64 v[146:147], v[176:177], 0, s[8:9]
	s_mov_b32 m0, s52
	s_nop 0
	global_load_lds_dwordx4 v[146:147], off
	v_lshl_add_u64 v[146:147], v[232:233], 0, s[8:9]
	s_mov_b32 m0, s53
	s_nop 0
	global_load_lds_dwordx4 v[146:147], off
	s_waitcnt vmcnt(8)
	s_waitcnt lgkmcnt(0)
	s_setprio 1
	s_barrier
	v_mfma_i32_16x16x64_i8 v[62:65], v[142:145], v[200:203], v[62:65]
	v_mfma_i32_16x16x64_i8 v[54:57], v[172:175], v[200:203], v[54:57]
	v_mfma_i32_16x16x64_i8 v[46:49], v[142:145], v[208:211], v[46:49]
	v_mfma_i32_16x16x64_i8 v[38:41], v[172:175], v[208:211], v[38:41]
	v_mfma_i32_16x16x64_i8 v[30:33], v[142:145], v[216:219], v[30:33]
	v_mfma_i32_16x16x64_i8 v[22:25], v[172:175], v[216:219], v[22:25]
	v_mfma_i32_16x16x64_i8 v[14:17], v[142:145], v[224:227], v[14:17]
	v_mfma_i32_16x16x64_i8 v[6:9], v[172:175], v[224:227], v[6:9]
	v_mfma_i32_16x16x64_i8 v[62:65], v[168:171], v[204:207], v[62:65]
	v_mfma_i32_16x16x64_i8 v[54:57], v[180:183], v[204:207], v[54:57]
	v_mfma_i32_16x16x64_i8 v[46:49], v[168:171], v[212:215], v[46:49]
	v_mfma_i32_16x16x64_i8 v[38:41], v[180:183], v[212:215], v[38:41]
	v_mfma_i32_16x16x64_i8 v[30:33], v[168:171], v[220:223], v[30:33]
	v_mfma_i32_16x16x64_i8 v[22:25], v[180:183], v[220:223], v[22:25]
	v_mfma_i32_16x16x64_i8 v[14:17], v[168:171], v[228:231], v[14:17]
	v_mfma_i32_16x16x64_i8 v[6:9], v[180:183], v[228:231], v[6:9]
	s_setprio 0
	s_setprio 1
	v_mfma_i32_16x16x64_i8 v[58:61], v[184:187], v[200:203], v[58:61]
	v_mfma_i32_16x16x64_i8 v[50:53], v[192:195], v[200:203], v[50:53]
	v_mfma_i32_16x16x64_i8 v[42:45], v[184:187], v[208:211], v[42:45]
	v_mfma_i32_16x16x64_i8 v[34:37], v[192:195], v[208:211], v[34:37]
	v_mfma_i32_16x16x64_i8 v[26:29], v[184:187], v[216:219], v[26:29]
	v_mfma_i32_16x16x64_i8 v[18:21], v[192:195], v[216:219], v[18:21]
	v_mfma_i32_16x16x64_i8 v[10:13], v[184:187], v[224:227], v[10:13]
	v_mfma_i32_16x16x64_i8 v[2:5], v[192:195], v[224:227], v[2:5]
	v_mfma_i32_16x16x64_i8 v[58:61], v[188:191], v[204:207], v[58:61]
	v_mfma_i32_16x16x64_i8 v[50:53], v[196:199], v[204:207], v[50:53]
	v_mfma_i32_16x16x64_i8 v[42:45], v[188:191], v[212:215], v[42:45]
	v_mfma_i32_16x16x64_i8 v[34:37], v[196:199], v[212:215], v[34:37]
	v_mfma_i32_16x16x64_i8 v[26:29], v[188:191], v[220:223], v[26:29]
	v_mfma_i32_16x16x64_i8 v[18:21], v[196:199], v[220:223], v[18:21]
	v_mfma_i32_16x16x64_i8 v[10:13], v[188:191], v[228:231], v[10:13]
	v_mfma_i32_16x16x64_i8 v[2:5], v[196:199], v[228:231], v[2:5]
	s_setprio 0
	s_barrier
	s_add_i32 s70, s70, 2
	s_add_u32 s30, s30, 0x100
	s_addc_u32 s31, s31, 0
	s_add_u32 s68, s68, 0x100
	s_addc_u32 s69, s69, 0
	s_cmp_gt_u32 s70, 29
	s_cbranch_scc0 .LBB0_1638
	s_and_b64 vcc, exec, s[10:11]
	s_cbranch_vccz .LBB0_1641
	s_barrier

.LBB0_1657:
	ds_read_b128 v[146:149], v165
	ds_read_b128 v[170:173], v165 offset:1024
	ds_read_b128 v[174:177], v165 offset:2048
	ds_read_b128 v[180:183], v165 offset:3072
	ds_read_b128 v[184:187], v167
	ds_read_b128 v[188:191], v167 offset:1024
	ds_read_b128 v[192:195], v167 offset:2048
	ds_read_b128 v[196:199], v167 offset:3072
	s_add_u32 s30, s28, 0xfff80080
	s_addc_u32 s31, s29, -1
	s_cmp_eq_u32 s68, 28
	s_cselect_b32 s35, s19, s31
	s_cselect_b32 s34, s27, s30
	s_cselect_b32 s31, s17, s67
	s_cselect_b32 s30, s65, s66
	v_lshl_add_u64 v[150:151], s[28:29], 0, v[138:139]
	s_add_i32 m0, s45, 0xc000
	ds_read_b128 v[200:203], v168
	ds_read_b128 v[204:207], v168 offset:1024
	ds_read_b128 v[208:211], v168 offset:2048
	ds_read_b128 v[212:215], v168 offset:3072
	ds_read_b128 v[216:219], v168 offset:4096
	ds_read_b128 v[220:223], v168 offset:5120
	ds_read_b128 v[224:227], v168 offset:6144
	ds_read_b128 v[228:231], v168 offset:7168
	global_load_lds_dwordx4 v[150:151], off
	v_lshl_add_u64 v[150:151], s[28:29], 0, v[140:141]
	s_add_i32 m0, s45, 0xe000
	s_nop 0
	global_load_lds_dwordx4 v[150:151], off
	s_waitcnt vmcnt(8)
	s_waitcnt lgkmcnt(0)
	s_setprio 1
	s_barrier
	v_mfma_i32_16x16x64_i8 v[126:129], v[146:149], v[200:203], v[126:129]
	v_mfma_i32_16x16x64_i8 v[118:121], v[174:177], v[200:203], v[118:121]
	v_mfma_i32_16x16x64_i8 v[110:113], v[146:149], v[208:211], v[110:113]
	v_mfma_i32_16x16x64_i8 v[102:105], v[174:177], v[208:211], v[102:105]
	v_mfma_i32_16x16x64_i8 v[94:97], v[146:149], v[216:219], v[94:97]
	v_mfma_i32_16x16x64_i8 v[86:89], v[174:177], v[216:219], v[86:89]
	v_mfma_i32_16x16x64_i8 v[78:81], v[146:149], v[224:227], v[78:81]
	v_mfma_i32_16x16x64_i8 v[70:73], v[174:177], v[224:227], v[70:73]
	v_mfma_i32_16x16x64_i8 v[126:129], v[170:173], v[204:207], v[126:129]
	v_mfma_i32_16x16x64_i8 v[118:121], v[180:183], v[204:207], v[118:121]
	v_mfma_i32_16x16x64_i8 v[110:113], v[170:173], v[212:215], v[110:113]
	v_mfma_i32_16x16x64_i8 v[102:105], v[180:183], v[212:215], v[102:105]
	v_mfma_i32_16x16x64_i8 v[94:97], v[170:173], v[220:223], v[94:97]
	v_mfma_i32_16x16x64_i8 v[86:89], v[180:183], v[220:223], v[86:89]
	v_mfma_i32_16x16x64_i8 v[78:81], v[170:173], v[228:231], v[78:81]
	v_mfma_i32_16x16x64_i8 v[70:73], v[180:183], v[228:231], v[70:73]
	s_setprio 0
	s_setprio 1
	v_mfma_i32_16x16x64_i8 v[122:125], v[184:187], v[200:203], v[122:125]
	v_mfma_i32_16x16x64_i8 v[114:117], v[192:195], v[200:203], v[114:117]
	v_mfma_i32_16x16x64_i8 v[106:109], v[184:187], v[208:211], v[106:109]
	v_mfma_i32_16x16x64_i8 v[98:101], v[192:195], v[208:211], v[98:101]
	v_mfma_i32_16x16x64_i8 v[90:93], v[184:187], v[216:219], v[90:93]
	v_mfma_i32_16x16x64_i8 v[82:85], v[192:195], v[216:219], v[82:85]
	v_mfma_i32_16x16x64_i8 v[74:77], v[184:187], v[224:227], v[74:77]
	v_mfma_i32_16x16x64_i8 v[66:69], v[192:195], v[224:227], v[66:69]
	v_mfma_i32_16x16x64_i8 v[122:125], v[188:191], v[204:207], v[122:125]
	v_mfma_i32_16x16x64_i8 v[114:117], v[196:199], v[204:207], v[114:117]
	v_mfma_i32_16x16x64_i8 v[106:109], v[188:191], v[212:215], v[106:109]
	v_mfma_i32_16x16x64_i8 v[98:101], v[196:199], v[212:215], v[98:101]
	v_mfma_i32_16x16x64_i8 v[90:93], v[188:191], v[220:223], v[90:93]
	v_mfma_i32_16x16x64_i8 v[82:85], v[196:199], v[220:223], v[82:85]
	v_mfma_i32_16x16x64_i8 v[74:77], v[188:191], v[228:231], v[74:77]
	v_mfma_i32_16x16x64_i8 v[66:69], v[196:199], v[228:231], v[66:69]
	s_setprio 0
	s_barrier
	s_add_i32 s69, s55, s15
	v_lshl_add_u64 v[150:151], s[30:31], 0, v[132:133]
	s_mov_b32 m0, s69
	ds_read_b128 v[200:203], v168 offset:16384
	ds_read_b128 v[204:207], v168 offset:17408
	ds_read_b128 v[208:211], v168 offset:18432
	ds_read_b128 v[212:215], v168 offset:19456
	ds_read_b128 v[216:219], v168 offset:20480
	ds_read_b128 v[220:223], v168 offset:21504
	ds_read_b128 v[224:227], v168 offset:22528
	ds_read_b128 v[228:231], v168 offset:23552
	global_load_lds_dwordx4 v[150:151], off
	s_add_i32 m0, s69, 0x2000
	s_add_u32 s70, s30, 0x80000
	v_lshl_add_u64 v[160:161], s[30:31], 0, v[136:137]
	s_addc_u32 s71, s31, 0
	s_add_i32 s69, s56, s15
	global_load_lds_dwordx4 v[160:161], off
	v_lshl_add_u64 v[232:233], s[70:71], 0, v[132:133]
	s_mov_b32 m0, s69
	v_lshl_add_u64 v[234:235], s[34:35], 0, v[134:135]
	global_load_lds_dwordx4 v[232:233], off
	v_lshl_add_u64 v[232:233], s[70:71], 0, v[136:137]
	s_add_i32 m0, s69, 0x2000
	s_nop 0
	global_load_lds_dwordx4 v[232:233], off
	v_lshl_add_u64 v[232:233], s[34:35], 0, v[130:131]
	s_mov_b32 m0, s45
	s_nop 0
	global_load_lds_dwordx4 v[232:233], off
	s_mov_b32 m0, s46
	s_nop 0
	global_load_lds_dwordx4 v[234:235], off
	s_waitcnt vmcnt(8)
	s_waitcnt lgkmcnt(0)
	s_setprio 1
	s_barrier
	v_mfma_i32_16x16x64_i8 v[62:65], v[146:149], v[200:203], v[62:65]
	v_mfma_i32_16x16x64_i8 v[54:57], v[174:177], v[200:203], v[54:57]
	v_mfma_i32_16x16x64_i8 v[46:49], v[146:149], v[208:211], v[46:49]
	v_mfma_i32_16x16x64_i8 v[38:41], v[174:177], v[208:211], v[38:41]
	v_mfma_i32_16x16x64_i8 v[30:33], v[146:149], v[216:219], v[30:33]
	v_mfma_i32_16x16x64_i8 v[22:25], v[174:177], v[216:219], v[22:25]
	v_mfma_i32_16x16x64_i8 v[14:17], v[146:149], v[224:227], v[14:17]
	v_mfma_i32_16x16x64_i8 v[6:9], v[174:177], v[224:227], v[6:9]
	v_mfma_i32_16x16x64_i8 v[62:65], v[170:173], v[204:207], v[62:65]
	v_mfma_i32_16x16x64_i8 v[54:57], v[180:183], v[204:207], v[54:57]
	v_mfma_i32_16x16x64_i8 v[46:49], v[170:173], v[212:215], v[46:49]
	v_mfma_i32_16x16x64_i8 v[38:41], v[180:183], v[212:215], v[38:41]
	v_mfma_i32_16x16x64_i8 v[30:33], v[170:173], v[220:223], v[30:33]
	v_mfma_i32_16x16x64_i8 v[22:25], v[180:183], v[220:223], v[22:25]
	v_mfma_i32_16x16x64_i8 v[14:17], v[170:173], v[228:231], v[14:17]
	v_mfma_i32_16x16x64_i8 v[6:9], v[180:183], v[228:231], v[6:9]
	s_setprio 0
	s_setprio 1
	v_mfma_i32_16x16x64_i8 v[58:61], v[184:187], v[200:203], v[58:61]
	v_mfma_i32_16x16x64_i8 v[50:53], v[192:195], v[200:203], v[50:53]
	v_mfma_i32_16x16x64_i8 v[42:45], v[184:187], v[208:211], v[42:45]
	v_mfma_i32_16x16x64_i8 v[34:37], v[192:195], v[208:211], v[34:37]
	v_mfma_i32_16x16x64_i8 v[26:29], v[184:187], v[216:219], v[26:29]
	v_mfma_i32_16x16x64_i8 v[18:21], v[192:195], v[216:219], v[18:21]
	v_mfma_i32_16x16x64_i8 v[10:13], v[184:187], v[224:227], v[10:13]
	v_mfma_i32_16x16x64_i8 v[2:5], v[192:195], v[224:227], v[2:5]
	v_mfma_i32_16x16x64_i8 v[58:61], v[188:191], v[204:207], v[58:61]
	v_mfma_i32_16x16x64_i8 v[50:53], v[196:199], v[204:207], v[50:53]
	v_mfma_i32_16x16x64_i8 v[42:45], v[188:191], v[212:215], v[42:45]
	v_mfma_i32_16x16x64_i8 v[34:37], v[196:199], v[212:215], v[34:37]
	v_mfma_i32_16x16x64_i8 v[26:29], v[188:191], v[220:223], v[26:29]
	v_mfma_i32_16x16x64_i8 v[18:21], v[196:199], v[220:223], v[18:21]
	v_mfma_i32_16x16x64_i8 v[10:13], v[188:191], v[228:231], v[10:13]
	v_mfma_i32_16x16x64_i8 v[2:5], v[196:199], v[228:231], v[2:5]
	s_setprio 0
	s_barrier
	s_add_i32 s69, 0, 0x18000
	v_add_u32_e32 v152, s69, v157
	s_add_i32 s70, 0, 0x1c000
	ds_read_b128 v[146:149], v152
	ds_read_b128 v[170:173], v152 offset:1024
	ds_read_b128 v[174:177], v152 offset:2048
	ds_read_b128 v[180:183], v152 offset:3072
	v_add_u32_e32 v152, s70, v157
	ds_read_b128 v[184:187], v152
	ds_read_b128 v[188:191], v152 offset:1024
	ds_read_b128 v[192:195], v152 offset:2048
	ds_read_b128 v[196:199], v152 offset:3072
	s_add_u32 s34, s34, 0x80000
	s_addc_u32 s35, s35, 0
	s_mov_b32 m0, s47
	v_lshl_add_u64 v[236:237], s[34:35], 0, v[130:131]
	ds_read_b128 v[200:203], v168 offset:32768
	ds_read_b128 v[204:207], v168 offset:33792
	ds_read_b128 v[208:211], v168 offset:34816
	ds_read_b128 v[212:215], v168 offset:35840
	ds_read_b128 v[216:219], v168 offset:36864
	ds_read_b128 v[220:223], v168 offset:37888
	ds_read_b128 v[224:227], v168 offset:38912
	ds_read_b128 v[228:231], v168 offset:39936
	global_load_lds_dwordx4 v[236:237], off
	v_lshl_add_u64 v[236:237], s[34:35], 0, v[134:135]
	s_mov_b32 m0, s48
	s_nop 0
	global_load_lds_dwordx4 v[236:237], off
	s_waitcnt vmcnt(8)
	s_waitcnt lgkmcnt(0)
	s_setprio 1
	s_barrier
	v_mfma_i32_16x16x64_i8 v[126:129], v[146:149], v[200:203], v[126:129]
	v_mfma_i32_16x16x64_i8 v[118:121], v[174:177], v[200:203], v[118:121]
	v_mfma_i32_16x16x64_i8 v[110:113], v[146:149], v[208:211], v[110:113]
	v_mfma_i32_16x16x64_i8 v[102:105], v[174:177], v[208:211], v[102:105]
	v_mfma_i32_16x16x64_i8 v[94:97], v[146:149], v[216:219], v[94:97]
	v_mfma_i32_16x16x64_i8 v[86:89], v[174:177], v[216:219], v[86:89]
	v_mfma_i32_16x16x64_i8 v[78:81], v[146:149], v[224:227], v[78:81]
	v_mfma_i32_16x16x64_i8 v[70:73], v[174:177], v[224:227], v[70:73]
	v_mfma_i32_16x16x64_i8 v[126:129], v[170:173], v[204:207], v[126:129]
	v_mfma_i32_16x16x64_i8 v[118:121], v[180:183], v[204:207], v[118:121]
	v_mfma_i32_16x16x64_i8 v[110:113], v[170:173], v[212:215], v[110:113]
	v_mfma_i32_16x16x64_i8 v[102:105], v[180:183], v[212:215], v[102:105]
	v_mfma_i32_16x16x64_i8 v[94:97], v[170:173], v[220:223], v[94:97]
	v_mfma_i32_16x16x64_i8 v[86:89], v[180:183], v[220:223], v[86:89]
	v_mfma_i32_16x16x64_i8 v[78:81], v[170:173], v[228:231], v[78:81]
	v_mfma_i32_16x16x64_i8 v[70:73], v[180:183], v[228:231], v[70:73]
	s_setprio 0
	s_setprio 1
	v_mfma_i32_16x16x64_i8 v[122:125], v[184:187], v[200:203], v[122:125]
	v_mfma_i32_16x16x64_i8 v[114:117], v[192:195], v[200:203], v[114:117]
	v_mfma_i32_16x16x64_i8 v[106:109], v[184:187], v[208:211], v[106:109]
	v_mfma_i32_16x16x64_i8 v[98:101], v[192:195], v[208:211], v[98:101]
	v_mfma_i32_16x16x64_i8 v[90:93], v[184:187], v[216:219], v[90:93]
	v_mfma_i32_16x16x64_i8 v[82:85], v[192:195], v[216:219], v[82:85]
	v_mfma_i32_16x16x64_i8 v[74:77], v[184:187], v[224:227], v[74:77]
	v_mfma_i32_16x16x64_i8 v[66:69], v[192:195], v[224:227], v[66:69]
	v_mfma_i32_16x16x64_i8 v[122:125], v[188:191], v[204:207], v[122:125]
	v_mfma_i32_16x16x64_i8 v[114:117], v[196:199], v[204:207], v[114:117]
	v_mfma_i32_16x16x64_i8 v[106:109], v[188:191], v[212:215], v[106:109]
	v_mfma_i32_16x16x64_i8 v[98:101], v[196:199], v[212:215], v[98:101]
	v_mfma_i32_16x16x64_i8 v[90:93], v[188:191], v[220:223], v[90:93]
	v_mfma_i32_16x16x64_i8 v[82:85], v[196:199], v[220:223], v[82:85]
	v_mfma_i32_16x16x64_i8 v[74:77], v[188:191], v[228:231], v[74:77]
	v_mfma_i32_16x16x64_i8 v[66:69], v[196:199], v[228:231], v[66:69]
	s_setprio 0
	s_barrier
	s_add_i32 s34, s69, s15
	v_lshl_add_u64 v[150:151], v[150:151], 0, s[10:11]
	s_mov_b32 m0, s34
	ds_read_b128 v[200:203], v168 offset:49152
	ds_read_b128 v[204:207], v168 offset:50176
	ds_read_b128 v[208:211], v168 offset:51200
	ds_read_b128 v[212:215], v168 offset:52224
	ds_read_b128 v[216:219], v168 offset:53248
	ds_read_b128 v[220:223], v168 offset:54272
	ds_read_b128 v[224:227], v168 offset:55296
	ds_read_b128 v[228:231], v168 offset:56320
	global_load_lds_dwordx4 v[150:151], off
	s_add_i32 m0, s34, 0x2000
	s_add_u32 s30, s30, 0x80080
	v_lshl_add_u64 v[150:151], v[160:161], 0, s[10:11]
	s_addc_u32 s31, s31, 0
	s_add_i32 s34, s70, s15
	global_load_lds_dwordx4 v[150:151], off
	v_lshl_add_u64 v[150:151], s[30:31], 0, v[132:133]
	s_mov_b32 m0, s34
	s_nop 0
	global_load_lds_dwordx4 v[150:151], off
	v_lshl_add_u64 v[150:151], s[30:31], 0, v[136:137]
	s_add_i32 m0, s34, 0x2000
	s_nop 0
	global_load_lds_dwordx4 v[150:151], off
	v_lshl_add_u64 v[150:151], v[232:233], 0, s[10:11]
	s_mov_b32 m0, s52
	s_nop 0
	global_load_lds_dwordx4 v[150:151], off
	v_lshl_add_u64 v[150:151], v[234:235], 0, s[10:11]
	s_mov_b32 m0, s53
	s_nop 0
	global_load_lds_dwordx4 v[150:151], off
	s_waitcnt vmcnt(8)
	s_waitcnt lgkmcnt(0)
	s_setprio 1
	s_barrier
	v_mfma_i32_16x16x64_i8 v[62:65], v[146:149], v[200:203], v[62:65]
	v_mfma_i32_16x16x64_i8 v[54:57], v[174:177], v[200:203], v[54:57]
	v_mfma_i32_16x16x64_i8 v[46:49], v[146:149], v[208:211], v[46:49]
	v_mfma_i32_16x16x64_i8 v[38:41], v[174:177], v[208:211], v[38:41]
	v_mfma_i32_16x16x64_i8 v[30:33], v[146:149], v[216:219], v[30:33]
	v_mfma_i32_16x16x64_i8 v[22:25], v[174:177], v[216:219], v[22:25]
	v_mfma_i32_16x16x64_i8 v[14:17], v[146:149], v[224:227], v[14:17]
	v_mfma_i32_16x16x64_i8 v[6:9], v[174:177], v[224:227], v[6:9]
	v_mfma_i32_16x16x64_i8 v[62:65], v[170:173], v[204:207], v[62:65]
	v_mfma_i32_16x16x64_i8 v[54:57], v[180:183], v[204:207], v[54:57]
	v_mfma_i32_16x16x64_i8 v[46:49], v[170:173], v[212:215], v[46:49]
	v_mfma_i32_16x16x64_i8 v[38:41], v[180:183], v[212:215], v[38:41]
	v_mfma_i32_16x16x64_i8 v[30:33], v[170:173], v[220:223], v[30:33]
	v_mfma_i32_16x16x64_i8 v[22:25], v[180:183], v[220:223], v[22:25]
	v_mfma_i32_16x16x64_i8 v[14:17], v[170:173], v[228:231], v[14:17]
	v_mfma_i32_16x16x64_i8 v[6:9], v[180:183], v[228:231], v[6:9]
	s_setprio 0
	s_setprio 1
	v_mfma_i32_16x16x64_i8 v[58:61], v[184:187], v[200:203], v[58:61]
	v_mfma_i32_16x16x64_i8 v[50:53], v[192:195], v[200:203], v[50:53]
	v_mfma_i32_16x16x64_i8 v[42:45], v[184:187], v[208:211], v[42:45]
	v_mfma_i32_16x16x64_i8 v[34:37], v[192:195], v[208:211], v[34:37]
	v_mfma_i32_16x16x64_i8 v[26:29], v[184:187], v[216:219], v[26:29]
	v_mfma_i32_16x16x64_i8 v[18:21], v[192:195], v[216:219], v[18:21]
	v_mfma_i32_16x16x64_i8 v[10:13], v[184:187], v[224:227], v[10:13]
	v_mfma_i32_16x16x64_i8 v[2:5], v[192:195], v[224:227], v[2:5]
	v_mfma_i32_16x16x64_i8 v[58:61], v[188:191], v[204:207], v[58:61]
	v_mfma_i32_16x16x64_i8 v[50:53], v[196:199], v[204:207], v[50:53]
	v_mfma_i32_16x16x64_i8 v[42:45], v[188:191], v[212:215], v[42:45]
	v_mfma_i32_16x16x64_i8 v[34:37], v[196:199], v[212:215], v[34:37]
	v_mfma_i32_16x16x64_i8 v[26:29], v[188:191], v[220:223], v[26:29]
	v_mfma_i32_16x16x64_i8 v[18:21], v[196:199], v[220:223], v[18:21]
	v_mfma_i32_16x16x64_i8 v[10:13], v[188:191], v[228:231], v[10:13]
	v_mfma_i32_16x16x64_i8 v[2:5], v[196:199], v[228:231], v[2:5]
	s_setprio 0
	s_barrier
	s_add_i32 s68, s68, 2
	s_add_u32 s28, s28, 0x100
	s_addc_u32 s29, s29, 0
	s_add_u32 s66, s66, 0x100
	s_addc_u32 s67, s67, 0
	s_cmp_gt_u32 s68, 29
	s_cbranch_scc0 .LBB0_1657
	s_and_b64 vcc, exec, s[12:13]
	s_cbranch_vccz .LBB0_1660
	s_barrier

.LBB0_1690:
	ds_read_b128 v[26:29], v181
	ds_read_b128 v[30:33], v181 offset:1024
	ds_read_b128 v[18:21], v181 offset:2048
	ds_read_b128 v[22:25], v181 offset:3072
	ds_read_b128 v[10:13], v182
	ds_read_b128 v[14:17], v182 offset:1024
	ds_read_b128 v[2:5], v182 offset:2048
	ds_read_b128 v[6:9], v182 offset:3072
	s_add_i32 s70, s42, 2
	s_add_u32 s43, s40, 0xffea8080
	s_addc_u32 s44, s41, -1
	s_cmp_eq_u32 s29, s42
	s_cselect_b32 s42, s34, s68
	s_cselect_b32 s45, s31, s44
	s_cselect_b32 s44, s30, s43
	s_cselect_b32 s43, s35, s69
	v_lshl_add_u64 v[208:209], s[40:41], 0, v[166:167]
	s_add_i32 m0, s48, 0xc000
	ds_read_b128 v[170:173], v183
	ds_read_b128 v[174:177], v183 offset:1024
	ds_read_b128 v[184:187], v183 offset:2048
	ds_read_b128 v[188:191], v183 offset:3072
	ds_read_b128 v[192:195], v183 offset:4096
	ds_read_b128 v[196:199], v183 offset:5120
	ds_read_b128 v[200:203], v183 offset:6144
	ds_read_b128 v[204:207], v183 offset:7168
	global_load_lds_dwordx4 v[208:209], off
	v_lshl_add_u64 v[208:209], s[40:41], 0, v[168:169]
	s_add_i32 m0, s48, 0xe000
	s_nop 0
	global_load_lds_dwordx4 v[208:209], off
	s_waitcnt vmcnt(8)
	s_waitcnt lgkmcnt(0)
	s_setprio 1
	s_barrier
	v_mfma_f32_16x16x128_f8f6f4 v[158:161], v[26:33], v[170:177], v[158:161]
	v_mfma_f32_16x16x128_f8f6f4 v[154:157], v[18:25], v[170:177], v[154:157]
	v_mfma_f32_16x16x128_f8f6f4 v[150:153], v[26:33], v[184:191], v[150:153]
	v_mfma_f32_16x16x128_f8f6f4 v[138:141], v[18:25], v[184:191], v[138:141]
	v_mfma_f32_16x16x128_f8f6f4 v[130:133], v[26:33], v[192:199], v[130:133]
	v_mfma_f32_16x16x128_f8f6f4 v[122:125], v[18:25], v[192:199], v[122:125]
	v_mfma_f32_16x16x128_f8f6f4 v[114:117], v[26:33], v[200:207], v[114:117]
	v_mfma_f32_16x16x128_f8f6f4 v[106:109], v[18:25], v[200:207], v[106:109]
	s_setprio 0
	s_setprio 1
	v_mfma_f32_16x16x128_f8f6f4 v[146:149], v[10:17], v[170:177], v[146:149]
	v_mfma_f32_16x16x128_f8f6f4 v[142:145], v[2:9], v[170:177], v[142:145]
	v_mfma_f32_16x16x128_f8f6f4 v[134:137], v[10:17], v[184:191], v[134:137]
	v_mfma_f32_16x16x128_f8f6f4 v[126:129], v[2:9], v[184:191], v[126:129]
	v_mfma_f32_16x16x128_f8f6f4 v[118:121], v[10:17], v[192:199], v[118:121]
	v_mfma_f32_16x16x128_f8f6f4 v[110:113], v[2:9], v[192:199], v[110:113]
	v_mfma_f32_16x16x128_f8f6f4 v[102:105], v[10:17], v[200:207], v[102:105]
	v_mfma_f32_16x16x128_f8f6f4 v[98:101], v[2:9], v[200:207], v[98:101]
	s_setprio 0
	s_barrier
	s_add_i32 s71, s60, s47
	v_lshl_add_u64 v[170:171], s[42:43], 0, v[164:165]
	s_mov_b32 m0, s71
	ds_read_b128 v[184:187], v183 offset:16384
	ds_read_b128 v[188:191], v183 offset:17408
	ds_read_b128 v[192:195], v183 offset:18432
	ds_read_b128 v[196:199], v183 offset:19456
	ds_read_b128 v[200:203], v183 offset:20480
	ds_read_b128 v[204:207], v183 offset:21504
	ds_read_b128 v[208:211], v183 offset:22528
	ds_read_b128 v[212:215], v183 offset:23552
	global_load_lds_dwordx4 v[170:171], off
	s_add_i32 m0, s71, 0x2000
	s_add_u32 s72, s42, 0x158000
	v_lshl_add_u64 v[172:173], s[42:43], 0, v[162:163]
	s_addc_u32 s73, s43, 0
	s_add_i32 s71, s61, s47
	global_load_lds_dwordx4 v[172:173], off
	v_lshl_add_u64 v[174:175], s[72:73], 0, v[164:165]
	s_mov_b32 m0, s71
	v_lshl_add_u64 v[176:177], s[44:45], 0, v[162:163]
	global_load_lds_dwordx4 v[174:175], off
	v_lshl_add_u64 v[174:175], s[72:73], 0, v[162:163]
	s_add_i32 m0, s71, 0x2000
	s_nop 0
	global_load_lds_dwordx4 v[174:175], off
	v_lshl_add_u64 v[174:175], s[44:45], 0, v[164:165]
	s_mov_b32 m0, s48
	s_nop 0
	global_load_lds_dwordx4 v[174:175], off
	s_mov_b32 m0, s49
	s_nop 0
	global_load_lds_dwordx4 v[176:177], off
	s_waitcnt vmcnt(8)
	s_waitcnt lgkmcnt(0)
	s_setprio 1
	s_barrier
	v_mfma_f32_16x16x128_f8f6f4 v[94:97], v[26:33], v[184:191], v[94:97]
	v_mfma_f32_16x16x128_f8f6f4 v[90:93], v[18:25], v[184:191], v[90:93]
	v_mfma_f32_16x16x128_f8f6f4 v[82:85], v[26:33], v[192:199], v[82:85]
	v_mfma_f32_16x16x128_f8f6f4 v[74:77], v[18:25], v[192:199], v[74:77]
	v_mfma_f32_16x16x128_f8f6f4 v[66:69], v[26:33], v[200:207], v[66:69]
	v_mfma_f32_16x16x128_f8f6f4 v[58:61], v[18:25], v[200:207], v[58:61]
	v_mfma_f32_16x16x128_f8f6f4 v[50:53], v[26:33], v[208:215], v[50:53]
	v_mfma_f32_16x16x128_f8f6f4 v[42:45], v[18:25], v[208:215], v[42:45]
	s_setprio 0
	s_setprio 1
	v_mfma_f32_16x16x128_f8f6f4 v[86:89], v[10:17], v[184:191], v[86:89]
	v_mfma_f32_16x16x128_f8f6f4 v[78:81], v[2:9], v[184:191], v[78:81]
	v_mfma_f32_16x16x128_f8f6f4 v[70:73], v[10:17], v[192:199], v[70:73]
	v_mfma_f32_16x16x128_f8f6f4 v[62:65], v[2:9], v[192:199], v[62:65]
	v_mfma_f32_16x16x128_f8f6f4 v[54:57], v[10:17], v[200:207], v[54:57]
	v_mfma_f32_16x16x128_f8f6f4 v[46:49], v[2:9], v[200:207], v[46:49]
	v_mfma_f32_16x16x128_f8f6f4 v[38:41], v[10:17], v[208:215], v[38:41]
	v_mfma_f32_16x16x128_f8f6f4 v[34:37], v[2:9], v[208:215], v[34:37]
	s_setprio 0
	s_barrier
	s_add_i32 s71, 0, 0x18000
	s_add_i32 s72, 0, 0x1c000
	v_add_u32_e32 v14, s71, v180
	v_add_u32_e32 v30, s72, v180
	ds_read_b128 v[2:5], v14
	ds_read_b128 v[6:9], v14 offset:1024
	ds_read_b128 v[10:13], v14 offset:2048
	ds_read_b128 v[14:17], v14 offset:3072
	ds_read_b128 v[18:21], v30
	ds_read_b128 v[22:25], v30 offset:1024
	ds_read_b128 v[26:29], v30 offset:2048
	ds_read_b128 v[30:33], v30 offset:3072
	s_add_u32 s44, s44, 0x158000
	s_addc_u32 s45, s45, 0
	s_mov_b32 m0, s50
	v_lshl_add_u64 v[216:217], s[44:45], 0, v[164:165]
	ds_read_b128 v[184:187], v183 offset:32768
	ds_read_b128 v[188:191], v183 offset:33792
	ds_read_b128 v[192:195], v183 offset:34816
	ds_read_b128 v[196:199], v183 offset:35840
	ds_read_b128 v[200:203], v183 offset:36864
	ds_read_b128 v[204:207], v183 offset:37888
	ds_read_b128 v[208:211], v183 offset:38912
	ds_read_b128 v[212:215], v183 offset:39936
	global_load_lds_dwordx4 v[216:217], off
	v_lshl_add_u64 v[216:217], s[44:45], 0, v[162:163]
	s_mov_b32 m0, s51
	s_nop 0
	global_load_lds_dwordx4 v[216:217], off
	s_waitcnt vmcnt(8)
	s_waitcnt lgkmcnt(0)
	s_setprio 1
	s_barrier
	v_mfma_f32_16x16x128_f8f6f4 v[158:161], v[2:9], v[184:191], v[158:161]
	v_mfma_f32_16x16x128_f8f6f4 v[154:157], v[10:17], v[184:191], v[154:157]
	v_mfma_f32_16x16x128_f8f6f4 v[150:153], v[2:9], v[192:199], v[150:153]
	v_mfma_f32_16x16x128_f8f6f4 v[138:141], v[10:17], v[192:199], v[138:141]
	v_mfma_f32_16x16x128_f8f6f4 v[130:133], v[2:9], v[200:207], v[130:133]
	v_mfma_f32_16x16x128_f8f6f4 v[122:125], v[10:17], v[200:207], v[122:125]
	v_mfma_f32_16x16x128_f8f6f4 v[114:117], v[2:9], v[208:215], v[114:117]
	v_mfma_f32_16x16x128_f8f6f4 v[106:109], v[10:17], v[208:215], v[106:109]
	s_setprio 0
	s_setprio 1
	v_mfma_f32_16x16x128_f8f6f4 v[146:149], v[18:25], v[184:191], v[146:149]
	v_mfma_f32_16x16x128_f8f6f4 v[142:145], v[26:33], v[184:191], v[142:145]
	v_mfma_f32_16x16x128_f8f6f4 v[134:137], v[18:25], v[192:199], v[134:137]
	v_mfma_f32_16x16x128_f8f6f4 v[126:129], v[26:33], v[192:199], v[126:129]
	v_mfma_f32_16x16x128_f8f6f4 v[118:121], v[18:25], v[200:207], v[118:121]
	v_mfma_f32_16x16x128_f8f6f4 v[110:113], v[26:33], v[200:207], v[110:113]
	v_mfma_f32_16x16x128_f8f6f4 v[102:105], v[18:25], v[208:215], v[102:105]
	v_mfma_f32_16x16x128_f8f6f4 v[98:101], v[26:33], v[208:215], v[98:101]
	s_setprio 0
	s_barrier
	s_add_i32 s44, s71, s47
	v_lshl_add_u64 v[170:171], v[170:171], 0, s[14:15]
	s_mov_b32 m0, s44
	ds_read_b128 v[184:187], v183 offset:49152
	ds_read_b128 v[188:191], v183 offset:50176
	ds_read_b128 v[192:195], v183 offset:51200
	ds_read_b128 v[196:199], v183 offset:52224
	ds_read_b128 v[200:203], v183 offset:53248
	ds_read_b128 v[204:207], v183 offset:54272
	ds_read_b128 v[208:211], v183 offset:55296
	ds_read_b128 v[212:215], v183 offset:56320
	global_load_lds_dwordx4 v[170:171], off
	s_add_i32 m0, s44, 0x2000
	s_add_u32 s42, s42, 0x158080
	v_lshl_add_u64 v[170:171], v[172:173], 0, s[14:15]
	s_addc_u32 s43, s43, 0
	s_add_i32 s44, s72, s47
	global_load_lds_dwordx4 v[170:171], off
	v_lshl_add_u64 v[170:171], s[42:43], 0, v[164:165]
	s_mov_b32 m0, s44
	s_nop 0
	global_load_lds_dwordx4 v[170:171], off
	v_lshl_add_u64 v[170:171], s[42:43], 0, v[162:163]
	s_add_i32 m0, s44, 0x2000
	s_nop 0
	global_load_lds_dwordx4 v[170:171], off
	v_lshl_add_u64 v[170:171], v[174:175], 0, s[14:15]
	s_mov_b32 m0, s57
	s_nop 0
	global_load_lds_dwordx4 v[170:171], off
	v_lshl_add_u64 v[170:171], v[176:177], 0, s[14:15]
	s_mov_b32 m0, s58
	s_nop 0
	global_load_lds_dwordx4 v[170:171], off
	s_waitcnt vmcnt(8)
	s_waitcnt lgkmcnt(0)
	s_setprio 1
	s_barrier
	v_mfma_f32_16x16x128_f8f6f4 v[94:97], v[2:9], v[184:191], v[94:97]
	v_mfma_f32_16x16x128_f8f6f4 v[90:93], v[10:17], v[184:191], v[90:93]
	v_mfma_f32_16x16x128_f8f6f4 v[82:85], v[2:9], v[192:199], v[82:85]
	v_mfma_f32_16x16x128_f8f6f4 v[74:77], v[10:17], v[192:199], v[74:77]
	v_mfma_f32_16x16x128_f8f6f4 v[66:69], v[2:9], v[200:207], v[66:69]
	v_mfma_f32_16x16x128_f8f6f4 v[58:61], v[10:17], v[200:207], v[58:61]
	v_mfma_f32_16x16x128_f8f6f4 v[50:53], v[2:9], v[208:215], v[50:53]
	v_mfma_f32_16x16x128_f8f6f4 v[42:45], v[10:17], v[208:215], v[42:45]
	s_setprio 0
	s_setprio 1
	v_mfma_f32_16x16x128_f8f6f4 v[86:89], v[18:25], v[184:191], v[86:89]
	v_mfma_f32_16x16x128_f8f6f4 v[78:81], v[26:33], v[184:191], v[78:81]
	v_mfma_f32_16x16x128_f8f6f4 v[70:73], v[18:25], v[192:199], v[70:73]
	v_mfma_f32_16x16x128_f8f6f4 v[62:65], v[26:33], v[192:199], v[62:65]
	v_mfma_f32_16x16x128_f8f6f4 v[54:57], v[18:25], v[200:207], v[54:57]
	v_mfma_f32_16x16x128_f8f6f4 v[46:49], v[26:33], v[200:207], v[46:49]
	v_mfma_f32_16x16x128_f8f6f4 v[38:41], v[18:25], v[208:215], v[38:41]
	v_mfma_f32_16x16x128_f8f6f4 v[34:37], v[26:33], v[208:215], v[34:37]
	s_setprio 0
	s_barrier
	s_add_u32 s40, s40, 0x100
	s_addc_u32 s41, s41, 0
	s_add_u32 s68, s68, 0x100
	s_addc_u32 s69, s69, 0
	s_cmp_ge_i32 s70, s39
	s_mov_b32 s42, s70
	s_cbranch_scc0 .LBB0_1690
	s_and_b64 vcc, exec, s[16:17]
	s_cbranch_vccz .LBB0_1693
	s_barrier

.LBB0_1780:
	ds_read_b128 v[24:27], v183
	ds_read_b128 v[28:31], v183 offset:1024
	ds_read_b128 v[16:19], v183 offset:2048
	ds_read_b128 v[20:23], v183 offset:3072
	ds_read_b128 v[8:11], v184
	ds_read_b128 v[12:15], v184 offset:1024
	ds_read_b128 v[0:3], v184 offset:2048
	ds_read_b128 v[4:7], v184 offset:3072
	s_add_u32 s28, s26, 0xffea8080
	s_addc_u32 s29, s27, -1
	s_cmpk_eq_i32 s56, 0x52
	s_cselect_b32 s31, s3, s29
	s_cselect_b32 s30, s2, s28
	s_cselect_b32 s29, s23, s55
	s_cselect_b32 s28, s22, s33
	v_lshl_add_u64 v[210:211], s[26:27], 0, v[164:165]
	s_add_i32 m0, s39, 0xc000
	ds_read_b128 v[172:175], v185
	ds_read_b128 v[176:179], v185 offset:1024
	ds_read_b128 v[186:189], v185 offset:2048
	ds_read_b128 v[190:193], v185 offset:3072
	ds_read_b128 v[194:197], v185 offset:4096
	ds_read_b128 v[198:201], v185 offset:5120
	ds_read_b128 v[202:205], v185 offset:6144
	ds_read_b128 v[206:209], v185 offset:7168
	global_load_lds_dwordx4 v[210:211], off
	v_lshl_add_u64 v[210:211], s[26:27], 0, v[166:167]
	s_add_i32 m0, s39, 0xe000
	s_nop 0
	global_load_lds_dwordx4 v[210:211], off
	s_waitcnt vmcnt(8)
	s_waitcnt lgkmcnt(0)
	s_setprio 1
	s_barrier
	v_mfma_f32_16x16x128_f8f6f4 v[156:159], v[24:31], v[172:179], v[156:159]
	v_mfma_f32_16x16x128_f8f6f4 v[152:155], v[16:23], v[172:179], v[152:155]
	v_mfma_f32_16x16x128_f8f6f4 v[148:151], v[24:31], v[186:193], v[148:151]
	v_mfma_f32_16x16x128_f8f6f4 v[136:139], v[16:23], v[186:193], v[136:139]
	v_mfma_f32_16x16x128_f8f6f4 v[128:131], v[24:31], v[194:201], v[128:131]
	v_mfma_f32_16x16x128_f8f6f4 v[120:123], v[16:23], v[194:201], v[120:123]
	v_mfma_f32_16x16x128_f8f6f4 v[112:115], v[24:31], v[202:209], v[112:115]
	v_mfma_f32_16x16x128_f8f6f4 v[104:107], v[16:23], v[202:209], v[104:107]
	s_setprio 0
	s_setprio 1
	v_mfma_f32_16x16x128_f8f6f4 v[144:147], v[8:15], v[172:179], v[144:147]
	v_mfma_f32_16x16x128_f8f6f4 v[140:143], v[0:7], v[172:179], v[140:143]
	v_mfma_f32_16x16x128_f8f6f4 v[132:135], v[8:15], v[186:193], v[132:135]
	v_mfma_f32_16x16x128_f8f6f4 v[124:127], v[0:7], v[186:193], v[124:127]
	v_mfma_f32_16x16x128_f8f6f4 v[116:119], v[8:15], v[194:201], v[116:119]
	v_mfma_f32_16x16x128_f8f6f4 v[108:111], v[0:7], v[194:201], v[108:111]
	v_mfma_f32_16x16x128_f8f6f4 v[100:103], v[8:15], v[202:209], v[100:103]
	v_mfma_f32_16x16x128_f8f6f4 v[96:99], v[0:7], v[202:209], v[96:99]
	s_setprio 0
	s_barrier
	s_add_i32 s57, s51, s38
	v_lshl_add_u64 v[172:173], s[28:29], 0, v[160:161]
	s_mov_b32 m0, s57
	ds_read_b128 v[186:189], v185 offset:16384
	ds_read_b128 v[190:193], v185 offset:17408
	ds_read_b128 v[194:197], v185 offset:18432
	ds_read_b128 v[198:201], v185 offset:19456
	ds_read_b128 v[202:205], v185 offset:20480
	ds_read_b128 v[206:209], v185 offset:21504
	ds_read_b128 v[210:213], v185 offset:22528
	ds_read_b128 v[214:217], v185 offset:23552
	global_load_lds_dwordx4 v[172:173], off
	s_add_i32 m0, s57, 0x2000
	s_add_u32 s58, s28, 0x158000
	v_lshl_add_u64 v[174:175], s[28:29], 0, v[162:163]
	s_addc_u32 s59, s29, 0
	s_add_i32 s57, s52, s38
	global_load_lds_dwordx4 v[174:175], off
	v_lshl_add_u64 v[176:177], s[58:59], 0, v[160:161]
	s_mov_b32 m0, s57
	v_lshl_add_u64 v[178:179], s[30:31], 0, v[162:163]
	global_load_lds_dwordx4 v[176:177], off
	v_lshl_add_u64 v[176:177], s[58:59], 0, v[162:163]
	s_add_i32 m0, s57, 0x2000
	s_nop 0
	global_load_lds_dwordx4 v[176:177], off
	v_lshl_add_u64 v[176:177], s[30:31], 0, v[160:161]
	s_mov_b32 m0, s39
	s_nop 0
	global_load_lds_dwordx4 v[176:177], off
	s_mov_b32 m0, s40
	s_nop 0
	global_load_lds_dwordx4 v[178:179], off
	s_waitcnt vmcnt(8)
	s_waitcnt lgkmcnt(0)
	s_setprio 1
	s_barrier
	v_mfma_f32_16x16x128_f8f6f4 v[92:95], v[24:31], v[186:193], v[92:95]
	v_mfma_f32_16x16x128_f8f6f4 v[88:91], v[16:23], v[186:193], v[88:91]
	v_mfma_f32_16x16x128_f8f6f4 v[80:83], v[24:31], v[194:201], v[80:83]
	v_mfma_f32_16x16x128_f8f6f4 v[72:75], v[16:23], v[194:201], v[72:75]
	v_mfma_f32_16x16x128_f8f6f4 v[64:67], v[24:31], v[202:209], v[64:67]
	v_mfma_f32_16x16x128_f8f6f4 v[56:59], v[16:23], v[202:209], v[56:59]
	v_mfma_f32_16x16x128_f8f6f4 v[48:51], v[24:31], v[210:217], v[48:51]
	v_mfma_f32_16x16x128_f8f6f4 v[40:43], v[16:23], v[210:217], v[40:43]
	s_setprio 0
	s_setprio 1
	v_mfma_f32_16x16x128_f8f6f4 v[84:87], v[8:15], v[186:193], v[84:87]
	v_mfma_f32_16x16x128_f8f6f4 v[76:79], v[0:7], v[186:193], v[76:79]
	v_mfma_f32_16x16x128_f8f6f4 v[68:71], v[8:15], v[194:201], v[68:71]
	v_mfma_f32_16x16x128_f8f6f4 v[60:63], v[0:7], v[194:201], v[60:63]
	v_mfma_f32_16x16x128_f8f6f4 v[52:55], v[8:15], v[202:209], v[52:55]
	v_mfma_f32_16x16x128_f8f6f4 v[44:47], v[0:7], v[202:209], v[44:47]
	v_mfma_f32_16x16x128_f8f6f4 v[36:39], v[8:15], v[210:217], v[36:39]
	v_mfma_f32_16x16x128_f8f6f4 v[32:35], v[0:7], v[210:217], v[32:35]
	s_setprio 0
	s_barrier
	s_add_i32 s57, 0, 0x18000
	s_add_i32 s58, 0, 0x1c000
	v_add_u32_e32 v12, s57, v182
	v_add_u32_e32 v28, s58, v182
	ds_read_b128 v[0:3], v12
	ds_read_b128 v[4:7], v12 offset:1024
	ds_read_b128 v[8:11], v12 offset:2048
	ds_read_b128 v[12:15], v12 offset:3072
	ds_read_b128 v[16:19], v28
	ds_read_b128 v[20:23], v28 offset:1024
	ds_read_b128 v[24:27], v28 offset:2048
	ds_read_b128 v[28:31], v28 offset:3072
	s_add_u32 s30, s30, 0x158000
	s_addc_u32 s31, s31, 0
	s_mov_b32 m0, s41
	v_lshl_add_u64 v[218:219], s[30:31], 0, v[160:161]
	ds_read_b128 v[186:189], v185 offset:32768
	ds_read_b128 v[190:193], v185 offset:33792
	ds_read_b128 v[194:197], v185 offset:34816
	ds_read_b128 v[198:201], v185 offset:35840
	ds_read_b128 v[202:205], v185 offset:36864
	ds_read_b128 v[206:209], v185 offset:37888
	ds_read_b128 v[210:213], v185 offset:38912
	ds_read_b128 v[214:217], v185 offset:39936
	global_load_lds_dwordx4 v[218:219], off
	v_lshl_add_u64 v[218:219], s[30:31], 0, v[162:163]
	s_mov_b32 m0, s42
	s_nop 0
	global_load_lds_dwordx4 v[218:219], off
	s_waitcnt vmcnt(8)
	s_waitcnt lgkmcnt(0)
	s_setprio 1
	s_barrier
	v_mfma_f32_16x16x128_f8f6f4 v[156:159], v[0:7], v[186:193], v[156:159]
	v_mfma_f32_16x16x128_f8f6f4 v[152:155], v[8:15], v[186:193], v[152:155]
	v_mfma_f32_16x16x128_f8f6f4 v[148:151], v[0:7], v[194:201], v[148:151]
	v_mfma_f32_16x16x128_f8f6f4 v[136:139], v[8:15], v[194:201], v[136:139]
	v_mfma_f32_16x16x128_f8f6f4 v[128:131], v[0:7], v[202:209], v[128:131]
	v_mfma_f32_16x16x128_f8f6f4 v[120:123], v[8:15], v[202:209], v[120:123]
	v_mfma_f32_16x16x128_f8f6f4 v[112:115], v[0:7], v[210:217], v[112:115]
	v_mfma_f32_16x16x128_f8f6f4 v[104:107], v[8:15], v[210:217], v[104:107]
	s_setprio 0
	s_setprio 1
	v_mfma_f32_16x16x128_f8f6f4 v[144:147], v[16:23], v[186:193], v[144:147]
	v_mfma_f32_16x16x128_f8f6f4 v[140:143], v[24:31], v[186:193], v[140:143]
	v_mfma_f32_16x16x128_f8f6f4 v[132:135], v[16:23], v[194:201], v[132:135]
	v_mfma_f32_16x16x128_f8f6f4 v[124:127], v[24:31], v[194:201], v[124:127]
	v_mfma_f32_16x16x128_f8f6f4 v[116:119], v[16:23], v[202:209], v[116:119]
	v_mfma_f32_16x16x128_f8f6f4 v[108:111], v[24:31], v[202:209], v[108:111]
	v_mfma_f32_16x16x128_f8f6f4 v[100:103], v[16:23], v[210:217], v[100:103]
	v_mfma_f32_16x16x128_f8f6f4 v[96:99], v[24:31], v[210:217], v[96:99]
	s_setprio 0
	s_barrier
	s_add_i32 s30, s57, s38
	v_lshl_add_u64 v[172:173], v[172:173], 0, s[8:9]
	s_mov_b32 m0, s30
	ds_read_b128 v[186:189], v185 offset:49152
	ds_read_b128 v[190:193], v185 offset:50176
	ds_read_b128 v[194:197], v185 offset:51200
	ds_read_b128 v[198:201], v185 offset:52224
	ds_read_b128 v[202:205], v185 offset:53248
	ds_read_b128 v[206:209], v185 offset:54272
	ds_read_b128 v[210:213], v185 offset:55296
	ds_read_b128 v[214:217], v185 offset:56320
	global_load_lds_dwordx4 v[172:173], off
	s_add_i32 m0, s30, 0x2000
	s_add_u32 s28, s28, 0x158080
	v_lshl_add_u64 v[172:173], v[174:175], 0, s[8:9]
	s_addc_u32 s29, s29, 0
	s_add_i32 s30, s58, s38
	global_load_lds_dwordx4 v[172:173], off
	v_lshl_add_u64 v[172:173], s[28:29], 0, v[160:161]
	s_mov_b32 m0, s30
	s_nop 0
	global_load_lds_dwordx4 v[172:173], off
	v_lshl_add_u64 v[172:173], s[28:29], 0, v[162:163]
	s_add_i32 m0, s30, 0x2000
	s_nop 0
	global_load_lds_dwordx4 v[172:173], off
	v_lshl_add_u64 v[172:173], v[176:177], 0, s[8:9]
	s_mov_b32 m0, s48
	s_nop 0
	global_load_lds_dwordx4 v[172:173], off
	v_lshl_add_u64 v[172:173], v[178:179], 0, s[8:9]
	s_mov_b32 m0, s49
	s_nop 0
	global_load_lds_dwordx4 v[172:173], off
	s_waitcnt vmcnt(8)
	s_waitcnt lgkmcnt(0)
	s_setprio 1
	s_barrier
	v_mfma_f32_16x16x128_f8f6f4 v[92:95], v[0:7], v[186:193], v[92:95]
	v_mfma_f32_16x16x128_f8f6f4 v[88:91], v[8:15], v[186:193], v[88:91]
	v_mfma_f32_16x16x128_f8f6f4 v[80:83], v[0:7], v[194:201], v[80:83]
	v_mfma_f32_16x16x128_f8f6f4 v[72:75], v[8:15], v[194:201], v[72:75]
	v_mfma_f32_16x16x128_f8f6f4 v[64:67], v[0:7], v[202:209], v[64:67]
	v_mfma_f32_16x16x128_f8f6f4 v[56:59], v[8:15], v[202:209], v[56:59]
	v_mfma_f32_16x16x128_f8f6f4 v[48:51], v[0:7], v[210:217], v[48:51]
	v_mfma_f32_16x16x128_f8f6f4 v[40:43], v[8:15], v[210:217], v[40:43]
	s_setprio 0
	s_setprio 1
	v_mfma_f32_16x16x128_f8f6f4 v[84:87], v[16:23], v[186:193], v[84:87]
	v_mfma_f32_16x16x128_f8f6f4 v[76:79], v[24:31], v[186:193], v[76:79]
	v_mfma_f32_16x16x128_f8f6f4 v[68:71], v[16:23], v[194:201], v[68:71]
	v_mfma_f32_16x16x128_f8f6f4 v[60:63], v[24:31], v[194:201], v[60:63]
	v_mfma_f32_16x16x128_f8f6f4 v[52:55], v[16:23], v[202:209], v[52:55]
	v_mfma_f32_16x16x128_f8f6f4 v[44:47], v[24:31], v[202:209], v[44:47]
	v_mfma_f32_16x16x128_f8f6f4 v[36:39], v[16:23], v[210:217], v[36:39]
	v_mfma_f32_16x16x128_f8f6f4 v[32:35], v[24:31], v[210:217], v[32:35]
	s_setprio 0
	s_barrier
	s_add_i32 s56, s56, 2
	s_add_u32 s26, s26, 0x100
	s_addc_u32 s27, s27, 0
	s_add_u32 s33, s33, 0x100
	s_addc_u32 s55, s55, 0
	s_cmpk_gt_u32 s56, 0x53
	s_cbranch_scc0 .LBB0_1780
	s_and_b64 vcc, exec, s[10:11]
	s_cbranch_vccz .LBB0_1783
	s_barrier
